# trimmed softmax VALU in MODE 0 attention loops: cheap deferred-max check, out-of-line rescale path, immediate row-sum update, natural V key order (no P permlane swaps)
# speedup vs baseline: 1.0047x; 1.0047x over previous
; __device__ __forceinline__ void partialSM(f32x16& p0, f32x16& p1, float& m_reg, float& alpha) {
;   constexpr float THR2 = THR * 1.4426950408889634f;
;   float pmax = p0[0];
; #pragma unroll
;   for (int r = 1; r < 16; ++r) pmax = fmaxf(pmax, p0[r]);
; #pragma unroll
;   for (int r = 0; r < 16; ++r) pmax = fmaxf(pmax, p1[r]);
;   { auto rr = __builtin_amdgcn_permlane32_swap(__float_as_uint(pmax), __float_as_uint(pmax), false, false);
;     pmax = fmaxf(__uint_as_float(rr[0]), __uint_as_float(rr[1])); }
;   float mn;
;   if (__builtin_expect(__all(pmax - m_reg <= THR2), 1)) { mn = m_reg; alpha = 1.f; }
;   else { mn = fmaxf(m_reg, pmax); alpha = __builtin_amdgcn_exp2f(m_reg - mn); m_reg = mn; }
; #pragma unroll
;   for (int r = 0; r < 16; ++r) { p0[r] -= mn; p1[r] -= mn; }
; #pragma unroll
;   for (int r = 0; r < 16; ++r) p0[r] = __builtin_amdgcn_exp2f(p0[r]);
; }
; __device__ __forceinline__ void finishSM(f32x16& p0, f32x16& p1, float alpha, float& l_reg, bf16x8& pa0, bf16x8& pa1, bf16x8& pa2, bf16x8& pa3) {
; #pragma unroll
;   for (int r = 0; r < 16; ++r) p1[r] = __builtin_amdgcn_exp2f(p1[r]);
;   float ps = 0;
; #pragma unroll
;   for (int r = 0; r < 16; ++r) ps += p0[r];
; #pragma unroll
;   for (int r = 0; r < 16; ++r) ps += p1[r];
;   { auto rr = __builtin_amdgcn_permlane32_swap(__float_as_uint(ps), __float_as_uint(ps), false, false);
;     ps = __uint_as_float(rr[0]) + __uint_as_float(rr[1]); }
;   l_reg = l_reg * alpha + ps;
;     ...
;   PK4(p0, 0, pa0); PK4(p0, 8, pa1); PK4(p1, 0, pa2); PK4(p1, 8, pa3);
;     ...
; }
.LBB0_332:
	s_mov_b32 s11, s9
	s_mov_b32 s9, s12
	v_max3_f32 v192, v64, v65, v66
	v_max3_f32 v192, v192, v67, v68
	v_max3_f32 v192, v192, v69, v70
	v_max3_f32 v192, v192, v71, v72
	v_max3_f32 v192, v192, v73, v74
	v_max3_f32 v192, v192, v75, v76
	v_max3_f32 v192, v192, v77, v78
	v_max3_f32 v192, v192, v79, v80
	v_max3_f32 v192, v192, v81, v82
	v_max3_f32 v192, v192, v83, v84
	v_max3_f32 v192, v192, v85, v86
	v_max3_f32 v192, v192, v87, v88
	v_max3_f32 v192, v192, v89, v90
	v_max3_f32 v192, v192, v91, v92
	v_max3_f32 v192, v192, v93, v94
	v_max_f32_e32 v192, v192, v95
	v_mov_b32_e32 v193, v192
	s_nop 1
	v_permlane32_swap_b32_e32 v192, v193
	v_max_f32_e32 v192, v192, v193
	v_sub_f32_e32 v193, v192, v223
	v_cmp_ge_f32_e32 vcc, s19, v193
	s_cmp_eq_u64 vcc, exec
	s_cbranch_scc0 .Lw1slow_g1a
	v_sub_f32_e32 v64, v64, v223
	v_exp_f32_e32 v64, v64
	v_sub_f32_e32 v65, v65, v223
	v_exp_f32_e32 v65, v65
	v_sub_f32_e32 v66, v66, v223
	v_exp_f32_e32 v66, v66
	v_add_f32_e32 v225, v65, v64
	v_sub_f32_e32 v67, v67, v223
	v_exp_f32_e32 v67, v67
	v_add_f32_e32 v225, v66, v225
	v_sub_f32_e32 v68, v68, v223
	v_exp_f32_e32 v68, v68
	v_add_f32_e32 v225, v67, v225
	v_sub_f32_e32 v69, v69, v223
	v_exp_f32_e32 v69, v69
	v_add_f32_e32 v225, v68, v225
	v_sub_f32_e32 v70, v70, v223
	v_exp_f32_e32 v70, v70
	v_add_f32_e32 v225, v69, v225
	v_sub_f32_e32 v71, v71, v223
	v_exp_f32_e32 v71, v71
	v_add_f32_e32 v225, v70, v225
	v_sub_f32_e32 v72, v72, v223
	v_exp_f32_e32 v72, v72
	v_add_f32_e32 v225, v71, v225
	v_sub_f32_e32 v73, v73, v223
	v_exp_f32_e32 v73, v73
	v_add_f32_e32 v225, v72, v225
	v_sub_f32_e32 v74, v74, v223
	v_exp_f32_e32 v74, v74
	v_add_f32_e32 v225, v73, v225
	v_sub_f32_e32 v75, v75, v223
	v_exp_f32_e32 v75, v75
	v_add_f32_e32 v225, v74, v225
	v_sub_f32_e32 v76, v76, v223
	v_exp_f32_e32 v192, v76
	v_add_f32_e32 v225, v75, v225
	v_sub_f32_e32 v77, v77, v223
	v_exp_f32_e32 v193, v77
	v_add_f32_e32 v225, v192, v225
	v_sub_f32_e32 v78, v78, v223
	v_exp_f32_e32 v194, v78
	v_add_f32_e32 v225, v193, v225
	v_sub_f32_e32 v79, v79, v223
	v_exp_f32_e32 v195, v79
	v_add_f32_e32 v225, v194, v225
	v_sub_f32_e32 v80, v80, v223
	v_exp_f32_e32 v80, v80
	v_add_f32_e32 v225, v195, v225
	v_sub_f32_e32 v81, v81, v223
	v_exp_f32_e32 v81, v81
	v_add_f32_e32 v225, v80, v225
	v_sub_f32_e32 v82, v82, v223
	v_exp_f32_e32 v82, v82
	v_add_f32_e32 v225, v81, v225
	v_sub_f32_e32 v83, v83, v223
	v_exp_f32_e32 v83, v83
	v_add_f32_e32 v225, v82, v225
	v_sub_f32_e32 v84, v84, v223
	v_exp_f32_e32 v84, v84
	v_add_f32_e32 v225, v83, v225
	v_sub_f32_e32 v85, v85, v223
	v_exp_f32_e32 v85, v85
	v_add_f32_e32 v225, v84, v225
	v_sub_f32_e32 v86, v86, v223
	v_exp_f32_e32 v86, v86
	v_add_f32_e32 v225, v85, v225
	v_sub_f32_e32 v87, v87, v223
	v_exp_f32_e32 v87, v87
	v_add_f32_e32 v225, v86, v225
	v_sub_f32_e32 v88, v88, v223
	v_exp_f32_e32 v88, v88
	v_add_f32_e32 v225, v87, v225
	v_sub_f32_e32 v89, v89, v223
	v_exp_f32_e32 v89, v89
	v_add_f32_e32 v225, v88, v225
	v_sub_f32_e32 v90, v90, v223
	v_exp_f32_e32 v90, v90
	v_add_f32_e32 v225, v89, v225
	v_sub_f32_e32 v91, v91, v223
	v_exp_f32_e32 v91, v91
	v_add_f32_e32 v225, v90, v225
	v_sub_f32_e32 v92, v92, v223
	v_exp_f32_e32 v92, v92
	v_add_f32_e32 v225, v91, v225
	v_sub_f32_e32 v93, v93, v223
	v_exp_f32_e32 v93, v93
	v_add_f32_e32 v225, v92, v225
	v_sub_f32_e32 v94, v94, v223
	v_exp_f32_e32 v94, v94
	v_add_f32_e32 v225, v93, v225
	v_sub_f32_e32 v95, v95, v223
	v_exp_f32_e32 v95, v95
	v_add_f32_e32 v225, v94, v225
	v_add_f32_e32 v225, v95, v225
	v_mov_b32_e32 v226, v225
	v_cvt_pk_bf16_f32 v76, v64, v65
	v_cvt_pk_bf16_f32 v77, v66, v67
	v_cvt_pk_bf16_f32 v78, v68, v69
	v_cvt_pk_bf16_f32 v79, v70, v71
	v_cvt_pk_bf16_f32 v72, v72, v73
	v_cvt_pk_bf16_f32 v73, v74, v75
	v_cvt_pk_bf16_f32 v74, v192, v193
	v_cvt_pk_bf16_f32 v75, v194, v195
	v_cvt_pk_bf16_f32 v68, v80, v81
	v_cvt_pk_bf16_f32 v69, v82, v83
	v_cvt_pk_bf16_f32 v70, v84, v85
	v_cvt_pk_bf16_f32 v71, v86, v87
	v_cvt_pk_bf16_f32 v64, v88, v89
	v_cvt_pk_bf16_f32 v65, v90, v91
	v_cvt_pk_bf16_f32 v66, v92, v93
	v_cvt_pk_bf16_f32 v67, v94, v95
	v_permlane32_swap_b32_e32 v225, v226
	v_add_f32_e32 v222, v222, v225
	v_add_f32_e32 v222, v222, v226
.Lw1join_g1a:
	s_add_i32 s12, s8, -3
	s_cmp_ge_u32 s12, s83
	s_cbranch_scc1 .LBB0_338
	s_lshl_b32 s12, s10, 14
	s_add_i32 s12, s12, 0
	v_add_u32_e32 v80, s12, v183
	v_add_u32_e32 v81, s12, v210
	v_add_u32_e32 v82, s12, v211
	v_add_u32_e32 v83, s12, v212
	s_waitcnt vmcnt(3)
	ds_write_b128 v80, v[148:151]
	s_waitcnt vmcnt(1)
	ds_write_b128 v81, v[152:155]
	s_waitcnt vmcnt(5)
	ds_write_b128 v82, v[156:159] offset:49152
	s_waitcnt vmcnt(0)
	ds_write_b128 v83, v[160:163] offset:49152

; #define VRDK(L, H, KS) do { _Pragma("unroll") for (int d0 = 0; d0 < 4; ++d0) { L[d0] = vtr(vp + v_rd_off(d0, KS, 0)); H[d0] = vtr(vp + v_rd_off(d0, KS, 1)); } } while (0)
; #define PVK(pa, L, H) do { _Pragma("unroll") for (int d0 = 0; d0 < 4; ++d0) o[d0] = __builtin_amdgcn_mfma_f32_32x32x16_bf16(pa, PK(L[d0], H[d0]), o[d0], 0, 0, 0); } while (0)
; template <int NQ, bool QREG> __device__ __forceinline__ void qkt(f32x16& p0, f32x16& p1, const bf16_t* Ks, const bf16x8* qr, const bf16_t* Qw, int r32, int hi, int qcolB) {
;   p0 = f32x16{}; p1 = f32x16{};
; #pragma unroll
;   for (int d0 = 0; d0 < NQ; ++d0) { int cb = qcolB + (d0 * 16 + hi * 8) * 2;
;     bf16x8 b0 = *reinterpret_cast<const bf16x8*>((const char*)Ks + KSWZ(r32, cb));
;     bf16x8 b1 = *reinterpret_cast<const bf16x8*>((const char*)Ks + KSWZ(32 + r32, cb));
;     const bf16x8 qv = QREG ? qr[d0] : ld8(Qw + d0 * 16);
;     p0 = __builtin_amdgcn_mfma_f32_32x32x16_bf16(b0, qv, p0, 0, 0, 0); p1 = __builtin_amdgcn_mfma_f32_32x32x16_bf16(b1, qv, p1, 0, 0, 0); }
;   if (QREG) { __builtin_amdgcn_sched_group_barrier(0x100, 2 * NQ, 0); __builtin_amdgcn_sched_group_barrier(0x008, 2 * NQ, 0); }
; }
; template <bool PIPE> __device__ __forceinline__ void pv_d0(f32x16* o, lds_cptr vp, bf16x8 pa0, bf16x8 pa1, bf16x8 pa2, bf16x8 pa3) {
;   s16x4 La[4], Ha[4], Lb[4], Hb[4];
;   if constexpr (!PIPE) {
;     VRDK(La, Ha, 0); PVK(pa0, La, Ha); VRDK(La, Ha, 1); PVK(pa1, La, Ha); VRDK(La, Ha, 2); PVK(pa2, La, Ha); VRDK(La, Ha, 3); PVK(pa3, La, Ha);
;     return;
;   }
;   VRDK(La, Ha, 0); VRDK(Lb, Hb, 1);
;   PVK(pa0, La, Ha); VRDK(La, Ha, 2);
;   PVK(pa1, Lb, Hb); VRDK(Lb, Hb, 3);
;   PVK(pa2, La, Ha); PVK(pa3, Lb, Hb);
;   __builtin_amdgcn_sched_group_barrier(0x100, 16, 0); __builtin_amdgcn_sched_group_barrier(0x008, 4, 0);
;   __builtin_amdgcn_sched_group_barrier(0x100, 8, 0);  __builtin_amdgcn_sched_group_barrier(0x008, 4, 0);
;   __builtin_amdgcn_sched_group_barrier(0x100, 8, 0);  __builtin_amdgcn_sched_group_barrier(0x008, 8, 0);
; }
.LBB0_340:
	s_lshl_b32 s12, s11, 14
	s_lshl_b32 s13, s9, 14
	s_add_i32 s14, s12, 0
	s_setprio 1
	v_add_u32_e32 v227, s13, v214
	ds_read_b64_tr_b16 v[80:81], v227
	ds_read_b64_tr_b16 v[82:83], v227 offset:2048
	ds_read_b64_tr_b16 v[84:85], v227 offset:512
	ds_read_b64_tr_b16 v[86:87], v227 offset:2560
	ds_read_b64_tr_b16 v[88:89], v227 offset:1024
	ds_read_b64_tr_b16 v[90:91], v227 offset:3072
	ds_read_b64_tr_b16 v[92:93], v227 offset:1536
	ds_read_b64_tr_b16 v[94:95], v227 offset:3584
	ds_read_b64_tr_b16 v[228:229], v227 offset:4096
	ds_read_b64_tr_b16 v[230:231], v227 offset:6144
	ds_read_b64_tr_b16 v[232:233], v227 offset:4608
	ds_read_b64_tr_b16 v[234:235], v227 offset:6656
	ds_read_b64_tr_b16 v[236:237], v227 offset:5120
	ds_read_b64_tr_b16 v[238:239], v227 offset:7168
	ds_read_b64_tr_b16 v[240:241], v227 offset:5632
	ds_read_b64_tr_b16 v[242:243], v227 offset:7680
	s_waitcnt lgkmcnt(14)
	v_mfma_f32_32x32x16_bf16 v[32:47], v[76:79], v[80:83], v[32:47]
	s_waitcnt lgkmcnt(12)
	v_mfma_f32_32x32x16_bf16 v[48:63], v[76:79], v[84:87], v[48:63]
	s_waitcnt lgkmcnt(10)
	v_mfma_f32_32x32x16_bf16 v[16:31], v[76:79], v[88:91], v[16:31]
	s_waitcnt lgkmcnt(8)
	v_mfma_f32_32x32x16_bf16 v[0:15], v[76:79], v[92:95], v[0:15]
	ds_read_b64_tr_b16 v[76:77], v227 offset:8192
	ds_read_b64_tr_b16 v[78:79], v227 offset:10240
	ds_read_b64_tr_b16 v[80:81], v227 offset:8704
	ds_read_b64_tr_b16 v[82:83], v227 offset:10752
	ds_read_b64_tr_b16 v[84:85], v227 offset:9216
	ds_read_b64_tr_b16 v[86:87], v227 offset:11264
	ds_read_b64_tr_b16 v[88:89], v227 offset:9728
	ds_read_b64_tr_b16 v[90:91], v227 offset:11776
	s_waitcnt lgkmcnt(14)
	v_mfma_f32_32x32x16_bf16 v[32:47], v[72:75], v[228:231], v[32:47]
	s_waitcnt lgkmcnt(12)
	v_mfma_f32_32x32x16_bf16 v[48:63], v[72:75], v[232:235], v[48:63]
	s_waitcnt lgkmcnt(10)
	v_mfma_f32_32x32x16_bf16 v[16:31], v[72:75], v[236:239], v[16:31]
	s_waitcnt lgkmcnt(8)
	v_mfma_f32_32x32x16_bf16 v[0:15], v[72:75], v[240:243], v[0:15]
	ds_read_b64_tr_b16 v[72:73], v227 offset:12288
	ds_read_b64_tr_b16 v[74:75], v227 offset:14336
	ds_read_b64_tr_b16 v[92:93], v227 offset:12800
	ds_read_b64_tr_b16 v[94:95], v227 offset:14848
	ds_read_b64_tr_b16 v[228:229], v227 offset:13312
	ds_read_b64_tr_b16 v[230:231], v227 offset:15360
	ds_read_b64_tr_b16 v[232:233], v227 offset:13824
	ds_read_b64_tr_b16 v[234:235], v227 offset:15872
	s_waitcnt lgkmcnt(14)
	v_mfma_f32_32x32x16_bf16 v[32:47], v[68:71], v[76:79], v[32:47]
	s_waitcnt lgkmcnt(12)
	v_mfma_f32_32x32x16_bf16 v[48:63], v[68:71], v[80:83], v[48:63]
	s_waitcnt lgkmcnt(10)
	v_mfma_f32_32x32x16_bf16 v[16:31], v[68:71], v[84:87], v[16:31]
	s_waitcnt lgkmcnt(8)
	v_mfma_f32_32x32x16_bf16 v[0:15], v[68:71], v[88:91], v[0:15]
	s_waitcnt lgkmcnt(6)
	v_mfma_f32_32x32x16_bf16 v[32:47], v[64:67], v[72:75], v[32:47]
	s_waitcnt lgkmcnt(4)
	v_mfma_f32_32x32x16_bf16 v[48:63], v[64:67], v[92:95], v[48:63]
	s_waitcnt lgkmcnt(2)
	v_mfma_f32_32x32x16_bf16 v[16:31], v[64:67], v[228:231], v[16:31]
	s_waitcnt lgkmcnt(0)
	v_mfma_f32_32x32x16_bf16 v[0:15], v[64:67], v[232:235], v[0:15]
	v_add_u32_e32 v68, s14, v218
	ds_read_b128 v[80:83], v68 offset:57344
	v_add_u32_e32 v227, s14, v219
	ds_read_b128 v[64:67], v68 offset:49152
	ds_read_b128 v[232:235], v227 offset:57344
	ds_read_b128 v[228:231], v227 offset:49152
	v_add_u32_e32 v227, s14, v220
	s_waitcnt lgkmcnt(3)
	v_mfma_f32_32x32x16_bf16 v[80:95], v[80:83], v[104:107], 0
	s_waitcnt lgkmcnt(1)
	v_mfma_f32_32x32x16_bf16 v[80:95], v[232:235], v[108:111], v[80:95]
	ds_read_b128 v[232:235], v227 offset:57344
	v_mfma_f32_32x32x16_bf16 v[64:79], v[64:67], v[104:107], 0
	s_waitcnt lgkmcnt(1)
	v_mfma_f32_32x32x16_bf16 v[64:79], v[228:231], v[108:111], v[64:79]
	ds_read_b128 v[228:231], v227 offset:49152
	v_add_u32_e32 v227, s14, v221
	s_waitcnt lgkmcnt(1)
	v_mfma_f32_32x32x16_bf16 v[80:95], v[232:235], v[112:115], v[80:95]
	ds_read_b128 v[232:235], v227 offset:57344
	s_waitcnt lgkmcnt(1)
	v_mfma_f32_32x32x16_bf16 v[64:79], v[228:231], v[112:115], v[64:79]
	ds_read_b128 v[228:231], v227 offset:49152
	s_waitcnt lgkmcnt(0)
	v_mfma_f32_32x32x16_bf16 v[64:79], v[228:231], v[100:103], v[64:79]
	v_mfma_f32_32x32x16_bf16 v[80:95], v[232:235], v[100:103], v[80:95]
	s_setprio 0
	s_waitcnt lgkmcnt(0)
	s_barrier
; __device__ __forceinline__ void partialSM(f32x16& p0, f32x16& p1, float& m_reg, float& alpha) {
;   constexpr float THR2 = THR * 1.4426950408889634f;
;   float pmax = p0[0];
; #pragma unroll
;   for (int r = 1; r < 16; ++r) pmax = fmaxf(pmax, p0[r]);
; #pragma unroll
;   for (int r = 0; r < 16; ++r) pmax = fmaxf(pmax, p1[r]);
;   { auto rr = __builtin_amdgcn_permlane32_swap(__float_as_uint(pmax), __float_as_uint(pmax), false, false);
;     pmax = fmaxf(__uint_as_float(rr[0]), __uint_as_float(rr[1])); }
;   float mn;
;   if (__builtin_expect(__all(pmax - m_reg <= THR2), 1)) { mn = m_reg; alpha = 1.f; }
;   else { mn = fmaxf(m_reg, pmax); alpha = __builtin_amdgcn_exp2f(m_reg - mn); m_reg = mn; }
; #pragma unroll
;   for (int r = 0; r < 16; ++r) { p0[r] -= mn; p1[r] -= mn; }
; #pragma unroll
;   for (int r = 0; r < 16; ++r) p0[r] = __builtin_amdgcn_exp2f(p0[r]);
; }
; __device__ __forceinline__ void finishSM(f32x16& p0, f32x16& p1, float alpha, float& l_reg, bf16x8& pa0, bf16x8& pa1, bf16x8& pa2, bf16x8& pa3) {
; #pragma unroll
;   for (int r = 0; r < 16; ++r) p1[r] = __builtin_amdgcn_exp2f(p1[r]);
;   float ps = 0;
; #pragma unroll
;   for (int r = 0; r < 16; ++r) ps += p0[r];
; #pragma unroll
;   for (int r = 0; r < 16; ++r) ps += p1[r];
;   { auto rr = __builtin_amdgcn_permlane32_swap(__float_as_uint(ps), __float_as_uint(ps), false, false);
;     ps = __uint_as_float(rr[0]) + __uint_as_float(rr[1]); }
;   l_reg = l_reg * alpha + ps;
;     ...
;   PK4(p0, 0, pa0); PK4(p0, 8, pa1); PK4(p1, 0, pa2); PK4(p1, 8, pa3);
;     ...
; }
	s_nop 9
	v_max3_f32 v227, v64, v65, v66
	v_max3_f32 v227, v227, v67, v68
	v_max3_f32 v227, v227, v69, v70
	v_max3_f32 v227, v227, v71, v72
	v_max3_f32 v227, v227, v73, v74
	v_max3_f32 v227, v227, v75, v76
	v_max3_f32 v227, v227, v77, v78
	v_max3_f32 v227, v227, v79, v80
	v_max3_f32 v227, v227, v81, v82
	v_max3_f32 v227, v227, v83, v84
	v_max3_f32 v227, v227, v85, v86
	v_max3_f32 v227, v227, v87, v88
	v_max3_f32 v227, v227, v89, v90
	v_max3_f32 v227, v227, v91, v92
	v_max3_f32 v227, v227, v93, v94
	v_max_f32_e32 v227, v227, v95
	v_mov_b32_e32 v228, v227
	s_nop 1
	v_permlane32_swap_b32_e32 v227, v228
	v_max_f32_e32 v227, v227, v228
	v_sub_f32_e32 v228, v227, v223
	v_cmp_ge_f32_e32 vcc, s19, v228
	s_cmp_eq_u64 vcc, exec
	s_cbranch_scc0 .Lw1slow_g1b
	v_sub_f32_e32 v64, v64, v223
	v_exp_f32_e32 v64, v64
	v_sub_f32_e32 v65, v65, v223
	v_exp_f32_e32 v65, v65
	v_sub_f32_e32 v66, v66, v223
	v_exp_f32_e32 v66, v66
	v_add_f32_e32 v246, v65, v64
	v_sub_f32_e32 v67, v67, v223
	v_exp_f32_e32 v67, v67
	v_add_f32_e32 v246, v66, v246
	v_sub_f32_e32 v68, v68, v223
	v_exp_f32_e32 v68, v68
	v_add_f32_e32 v246, v67, v246
	v_sub_f32_e32 v69, v69, v223
	v_exp_f32_e32 v69, v69
	v_add_f32_e32 v246, v68, v246
	v_sub_f32_e32 v70, v70, v223
	v_exp_f32_e32 v70, v70
	v_add_f32_e32 v246, v69, v246
	v_sub_f32_e32 v71, v71, v223
	v_exp_f32_e32 v71, v71
	v_add_f32_e32 v246, v70, v246
	v_sub_f32_e32 v72, v72, v223
	v_exp_f32_e32 v72, v72
	v_add_f32_e32 v246, v71, v246
	v_sub_f32_e32 v73, v73, v223
	v_exp_f32_e32 v73, v73
	v_add_f32_e32 v246, v72, v246
	v_sub_f32_e32 v74, v74, v223
	v_exp_f32_e32 v74, v74
	v_add_f32_e32 v246, v73, v246
	v_sub_f32_e32 v75, v75, v223
	v_exp_f32_e32 v75, v75
	v_add_f32_e32 v246, v74, v246
	v_sub_f32_e32 v76, v76, v223
	v_exp_f32_e32 v228, v76
	v_add_f32_e32 v246, v75, v246
	v_sub_f32_e32 v77, v77, v223
	v_exp_f32_e32 v229, v77
	v_add_f32_e32 v246, v228, v246
	v_sub_f32_e32 v78, v78, v223
	v_exp_f32_e32 v230, v78
	v_add_f32_e32 v246, v229, v246
	v_sub_f32_e32 v79, v79, v223
	v_exp_f32_e32 v231, v79
	v_add_f32_e32 v246, v230, v246
	v_sub_f32_e32 v80, v80, v223
	v_exp_f32_e32 v80, v80
	v_add_f32_e32 v246, v231, v246
	v_sub_f32_e32 v81, v81, v223
	v_exp_f32_e32 v81, v81
	v_add_f32_e32 v246, v80, v246
	v_sub_f32_e32 v82, v82, v223
	v_exp_f32_e32 v82, v82
	v_add_f32_e32 v246, v81, v246
	v_sub_f32_e32 v83, v83, v223
	v_exp_f32_e32 v83, v83
	v_add_f32_e32 v246, v82, v246
	v_sub_f32_e32 v84, v84, v223
	v_exp_f32_e32 v84, v84
	v_add_f32_e32 v246, v83, v246
	v_sub_f32_e32 v85, v85, v223
	v_exp_f32_e32 v85, v85
	v_add_f32_e32 v246, v84, v246
	v_sub_f32_e32 v86, v86, v223
	v_exp_f32_e32 v86, v86
	v_add_f32_e32 v246, v85, v246
	v_sub_f32_e32 v87, v87, v223
	v_exp_f32_e32 v87, v87
	v_add_f32_e32 v246, v86, v246
	v_sub_f32_e32 v88, v88, v223
	v_exp_f32_e32 v88, v88
	v_add_f32_e32 v246, v87, v246
	v_sub_f32_e32 v89, v89, v223
	v_exp_f32_e32 v89, v89
	v_add_f32_e32 v246, v88, v246
	v_sub_f32_e32 v90, v90, v223
	v_exp_f32_e32 v90, v90
	v_add_f32_e32 v246, v89, v246
	v_sub_f32_e32 v91, v91, v223
	v_exp_f32_e32 v91, v91
	v_add_f32_e32 v246, v90, v246
	v_sub_f32_e32 v92, v92, v223
	v_exp_f32_e32 v92, v92
	v_add_f32_e32 v246, v91, v246
	v_sub_f32_e32 v93, v93, v223
	v_exp_f32_e32 v93, v93
	v_add_f32_e32 v246, v92, v246
	v_sub_f32_e32 v94, v94, v223
	v_exp_f32_e32 v94, v94
	v_add_f32_e32 v246, v93, v246
	v_sub_f32_e32 v95, v95, v223
	v_exp_f32_e32 v95, v95
	v_add_f32_e32 v246, v94, v246
	v_add_f32_e32 v246, v95, v246
	v_mov_b32_e32 v247, v246
	v_cvt_pk_bf16_f32 v76, v64, v65
	v_cvt_pk_bf16_f32 v77, v66, v67
	v_cvt_pk_bf16_f32 v78, v68, v69
	v_cvt_pk_bf16_f32 v79, v70, v71
	v_cvt_pk_bf16_f32 v72, v72, v73
	v_cvt_pk_bf16_f32 v73, v74, v75
	v_cvt_pk_bf16_f32 v74, v228, v229
	v_cvt_pk_bf16_f32 v75, v230, v231
	v_cvt_pk_bf16_f32 v68, v80, v81
	v_cvt_pk_bf16_f32 v69, v82, v83
	v_cvt_pk_bf16_f32 v70, v84, v85
	v_cvt_pk_bf16_f32 v71, v86, v87
	v_cvt_pk_bf16_f32 v64, v88, v89
	v_cvt_pk_bf16_f32 v65, v90, v91
	v_cvt_pk_bf16_f32 v66, v92, v93
	v_cvt_pk_bf16_f32 v67, v94, v95
	v_permlane32_swap_b32_e32 v246, v247
	v_add_f32_e32 v222, v222, v246
	v_add_f32_e32 v222, v222, v247
.Lw1join_g1b:
	s_add_i32 s34, s8, -2
	s_cmp_ge_u32 s34, s83
	s_cbranch_scc1 .LBB0_346
	s_add_i32 s13, s13, 0
	v_add_u32_e32 v82, s13, v183
	v_add_u32_e32 v83, s13, v210
	v_add_u32_e32 v84, s13, v211
	v_add_u32_e32 v85, s13, v212
	s_waitcnt vmcnt(3)
	ds_write_b128 v82, v[164:167]
	s_waitcnt vmcnt(1)
	ds_write_b128 v83, v[168:171]
	s_waitcnt vmcnt(1)
	ds_write_b128 v84, v[172:175] offset:49152
	s_waitcnt vmcnt(0)
	ds_write_b128 v85, v[176:179] offset:49152

; #define VRDK(L, H, KS) do { _Pragma("unroll") for (int d0 = 0; d0 < 4; ++d0) { L[d0] = vtr(vp + v_rd_off(d0, KS, 0)); H[d0] = vtr(vp + v_rd_off(d0, KS, 1)); } } while (0)
; #define PVK(pa, L, H) do { _Pragma("unroll") for (int d0 = 0; d0 < 4; ++d0) o[d0] = __builtin_amdgcn_mfma_f32_32x32x16_bf16(pa, PK(L[d0], H[d0]), o[d0], 0, 0, 0); } while (0)
; template <int NQ, bool QREG> __device__ __forceinline__ void qkt(f32x16& p0, f32x16& p1, const bf16_t* Ks, const bf16x8* qr, const bf16_t* Qw, int r32, int hi, int qcolB) {
;   p0 = f32x16{}; p1 = f32x16{};
; #pragma unroll
;   for (int d0 = 0; d0 < NQ; ++d0) { int cb = qcolB + (d0 * 16 + hi * 8) * 2;
;     bf16x8 b0 = *reinterpret_cast<const bf16x8*>((const char*)Ks + KSWZ(r32, cb));
;     bf16x8 b1 = *reinterpret_cast<const bf16x8*>((const char*)Ks + KSWZ(32 + r32, cb));
;     const bf16x8 qv = QREG ? qr[d0] : ld8(Qw + d0 * 16);
;     p0 = __builtin_amdgcn_mfma_f32_32x32x16_bf16(b0, qv, p0, 0, 0, 0); p1 = __builtin_amdgcn_mfma_f32_32x32x16_bf16(b1, qv, p1, 0, 0, 0); }
;   if (QREG) { __builtin_amdgcn_sched_group_barrier(0x100, 2 * NQ, 0); __builtin_amdgcn_sched_group_barrier(0x008, 2 * NQ, 0); }
; }
; template <bool PIPE> __device__ __forceinline__ void pv_d0(f32x16* o, lds_cptr vp, bf16x8 pa0, bf16x8 pa1, bf16x8 pa2, bf16x8 pa3) {
;   s16x4 La[4], Ha[4], Lb[4], Hb[4];
;   if constexpr (!PIPE) {
;     VRDK(La, Ha, 0); PVK(pa0, La, Ha); VRDK(La, Ha, 1); PVK(pa1, La, Ha); VRDK(La, Ha, 2); PVK(pa2, La, Ha); VRDK(La, Ha, 3); PVK(pa3, La, Ha);
;     return;
;   }
;   VRDK(La, Ha, 0); VRDK(Lb, Hb, 1);
;   PVK(pa0, La, Ha); VRDK(La, Ha, 2);
;   PVK(pa1, Lb, Hb); VRDK(Lb, Hb, 3);
;   PVK(pa2, La, Ha); PVK(pa3, Lb, Hb);
;   __builtin_amdgcn_sched_group_barrier(0x100, 16, 0); __builtin_amdgcn_sched_group_barrier(0x008, 4, 0);
;   __builtin_amdgcn_sched_group_barrier(0x100, 8, 0);  __builtin_amdgcn_sched_group_barrier(0x008, 4, 0);
;   __builtin_amdgcn_sched_group_barrier(0x100, 8, 0);  __builtin_amdgcn_sched_group_barrier(0x008, 8, 0);
; }
.LBB0_348:
	s_lshl_b32 s13, s10, 14
	s_add_i32 s14, s13, 0
	s_setprio 1
	v_add_u32_e32 v236, s12, v214
	ds_read_b64_tr_b16 v[80:81], v236
	ds_read_b64_tr_b16 v[82:83], v236 offset:2048
	ds_read_b64_tr_b16 v[84:85], v236 offset:512
	ds_read_b64_tr_b16 v[86:87], v236 offset:2560
	ds_read_b64_tr_b16 v[88:89], v236 offset:1024
	ds_read_b64_tr_b16 v[90:91], v236 offset:3072
	ds_read_b64_tr_b16 v[92:93], v236 offset:1536
	ds_read_b64_tr_b16 v[94:95], v236 offset:3584
	ds_read_b64_tr_b16 v[192:193], v236 offset:4096
	ds_read_b64_tr_b16 v[194:195], v236 offset:6144
	ds_read_b64_tr_b16 v[224:225], v236 offset:4608
	ds_read_b64_tr_b16 v[226:227], v236 offset:6656
	ds_read_b64_tr_b16 v[228:229], v236 offset:5120
	ds_read_b64_tr_b16 v[230:231], v236 offset:7168
	ds_read_b64_tr_b16 v[232:233], v236 offset:5632
	ds_read_b64_tr_b16 v[234:235], v236 offset:7680
	s_waitcnt lgkmcnt(14)
	v_mfma_f32_32x32x16_bf16 v[32:47], v[76:79], v[80:83], v[32:47]
	s_waitcnt lgkmcnt(12)
	v_mfma_f32_32x32x16_bf16 v[48:63], v[76:79], v[84:87], v[48:63]
	s_waitcnt lgkmcnt(10)
	v_mfma_f32_32x32x16_bf16 v[16:31], v[76:79], v[88:91], v[16:31]
	s_waitcnt lgkmcnt(8)
	v_mfma_f32_32x32x16_bf16 v[0:15], v[76:79], v[92:95], v[0:15]
	ds_read_b64_tr_b16 v[76:77], v236 offset:8192
	ds_read_b64_tr_b16 v[78:79], v236 offset:10240
	ds_read_b64_tr_b16 v[80:81], v236 offset:8704
	ds_read_b64_tr_b16 v[82:83], v236 offset:10752
	ds_read_b64_tr_b16 v[84:85], v236 offset:9216
	ds_read_b64_tr_b16 v[86:87], v236 offset:11264
	ds_read_b64_tr_b16 v[88:89], v236 offset:9728
	ds_read_b64_tr_b16 v[90:91], v236 offset:11776
	s_waitcnt lgkmcnt(14)
	v_mfma_f32_32x32x16_bf16 v[32:47], v[72:75], v[192:195], v[32:47]
	s_waitcnt lgkmcnt(12)
	v_mfma_f32_32x32x16_bf16 v[48:63], v[72:75], v[224:227], v[48:63]
	s_waitcnt lgkmcnt(10)
	v_mfma_f32_32x32x16_bf16 v[16:31], v[72:75], v[228:231], v[16:31]
	s_waitcnt lgkmcnt(8)
	v_mfma_f32_32x32x16_bf16 v[0:15], v[72:75], v[232:235], v[0:15]
	ds_read_b64_tr_b16 v[72:73], v236 offset:12288
	ds_read_b64_tr_b16 v[74:75], v236 offset:14336
	ds_read_b64_tr_b16 v[92:93], v236 offset:12800
	ds_read_b64_tr_b16 v[94:95], v236 offset:14848
	ds_read_b64_tr_b16 v[192:193], v236 offset:13312
	ds_read_b64_tr_b16 v[194:195], v236 offset:15360
	ds_read_b64_tr_b16 v[224:225], v236 offset:13824
	ds_read_b64_tr_b16 v[226:227], v236 offset:15872
	s_waitcnt lgkmcnt(14)
	v_mfma_f32_32x32x16_bf16 v[32:47], v[68:71], v[76:79], v[32:47]
	s_waitcnt lgkmcnt(12)
	v_mfma_f32_32x32x16_bf16 v[48:63], v[68:71], v[80:83], v[48:63]
	s_waitcnt lgkmcnt(10)
	v_mfma_f32_32x32x16_bf16 v[16:31], v[68:71], v[84:87], v[16:31]
	s_waitcnt lgkmcnt(8)
	v_mfma_f32_32x32x16_bf16 v[0:15], v[68:71], v[88:91], v[0:15]
	s_waitcnt lgkmcnt(6)
	v_mfma_f32_32x32x16_bf16 v[32:47], v[64:67], v[72:75], v[32:47]
	s_waitcnt lgkmcnt(4)
	v_mfma_f32_32x32x16_bf16 v[48:63], v[64:67], v[92:95], v[48:63]
	s_waitcnt lgkmcnt(2)
	v_mfma_f32_32x32x16_bf16 v[16:31], v[64:67], v[192:195], v[16:31]
	s_waitcnt lgkmcnt(0)
	v_mfma_f32_32x32x16_bf16 v[0:15], v[64:67], v[224:227], v[0:15]
	v_add_u32_e32 v68, s14, v218
	ds_read_b128 v[80:83], v68 offset:57344
	ds_read_b128 v[64:67], v68 offset:49152
	v_add_u32_e32 v224, s14, v219
	ds_read_b128 v[192:195], v224 offset:49152
	ds_read_b128 v[224:227], v224 offset:57344
	s_waitcnt lgkmcnt(3)
	v_mfma_f32_32x32x16_bf16 v[80:95], v[80:83], v[104:107], 0
	s_waitcnt lgkmcnt(2)
	v_mfma_f32_32x32x16_bf16 v[64:79], v[64:67], v[104:107], 0
	s_waitcnt lgkmcnt(0)
	v_mfma_f32_32x32x16_bf16 v[80:95], v[224:227], v[108:111], v[80:95]
	v_add_u32_e32 v224, s14, v220
	v_mfma_f32_32x32x16_bf16 v[64:79], v[192:195], v[108:111], v[64:79]
	ds_read_b128 v[192:195], v224 offset:49152
	ds_read_b128 v[224:227], v224 offset:57344
	s_waitcnt lgkmcnt(0)
	v_mfma_f32_32x32x16_bf16 v[80:95], v[224:227], v[112:115], v[80:95]
	v_add_u32_e32 v224, s14, v221
	v_mfma_f32_32x32x16_bf16 v[64:79], v[192:195], v[112:115], v[64:79]
	ds_read_b128 v[192:195], v224 offset:49152
	ds_read_b128 v[224:227], v224 offset:57344
	s_waitcnt lgkmcnt(1)
	v_mfma_f32_32x32x16_bf16 v[64:79], v[192:195], v[100:103], v[64:79]
	s_waitcnt lgkmcnt(0)
	v_mfma_f32_32x32x16_bf16 v[80:95], v[224:227], v[100:103], v[80:95]
	s_setprio 0
	s_add_i32 s8, s8, 2
	s_add_u32 s0, s0, 0x240000
	s_waitcnt lgkmcnt(0)
	s_barrier
	s_addc_u32 s1, s1, 0
	s_cmp_ge_u32 s34, s83
	s_cbranch_scc1 .LBB0_350
	s_mov_b32 s12, s10
	s_mov_b32 s10, s11
	s_branch .LBB0_332

; __device__ __forceinline__ void partialSM(f32x16& p0, f32x16& p1, float& m_reg, float& alpha) {
;   constexpr float THR2 = THR * 1.4426950408889634f;
;   float pmax = p0[0];
; #pragma unroll
;   for (int r = 1; r < 16; ++r) pmax = fmaxf(pmax, p0[r]);
; #pragma unroll
;   for (int r = 0; r < 16; ++r) pmax = fmaxf(pmax, p1[r]);
;   { auto rr = __builtin_amdgcn_permlane32_swap(__float_as_uint(pmax), __float_as_uint(pmax), false, false);
;     pmax = fmaxf(__uint_as_float(rr[0]), __uint_as_float(rr[1])); }
;   float mn;
;   if (__builtin_expect(__all(pmax - m_reg <= THR2), 1)) { mn = m_reg; alpha = 1.f; }
;   else { mn = fmaxf(m_reg, pmax); alpha = __builtin_amdgcn_exp2f(m_reg - mn); m_reg = mn; }
; #pragma unroll
;   for (int r = 0; r < 16; ++r) { p0[r] -= mn; p1[r] -= mn; }
; #pragma unroll
;   for (int r = 0; r < 16; ++r) p0[r] = __builtin_amdgcn_exp2f(p0[r]);
; }
; __device__ __forceinline__ void finishSM(f32x16& p0, f32x16& p1, float alpha, float& l_reg, bf16x8& pa0, bf16x8& pa1, bf16x8& pa2, bf16x8& pa3) {
; #pragma unroll
;   for (int r = 0; r < 16; ++r) p1[r] = __builtin_amdgcn_exp2f(p1[r]);
;   float ps = 0;
; #pragma unroll
;   for (int r = 0; r < 16; ++r) ps += p0[r];
; #pragma unroll
;   for (int r = 0; r < 16; ++r) ps += p1[r];
;   { auto rr = __builtin_amdgcn_permlane32_swap(__float_as_uint(ps), __float_as_uint(ps), false, false);
;     ps = __uint_as_float(rr[0]) + __uint_as_float(rr[1]); }
;   l_reg = l_reg * alpha + ps;
;     ...
;   PK4(p0, 0, pa0); PK4(p0, 8, pa1); PK4(p1, 0, pa2); PK4(p1, 8, pa3);
;     ...
; }
.LBB0_362:
	s_nop 1
	v_max3_f32 v161, v64, v65, v66
	v_max3_f32 v161, v161, v67, v68
	v_max3_f32 v161, v161, v69, v70
	v_max3_f32 v161, v161, v71, v72
	v_max3_f32 v161, v161, v73, v74
	v_max3_f32 v161, v161, v75, v76
	v_max3_f32 v161, v161, v77, v78
	v_max3_f32 v161, v161, v79, v80
	v_max3_f32 v161, v161, v81, v82
	v_max3_f32 v161, v161, v83, v84
	v_max3_f32 v161, v161, v85, v86
	v_max3_f32 v161, v161, v87, v88
	v_max3_f32 v161, v161, v89, v90
	v_max3_f32 v161, v161, v91, v92
	v_max3_f32 v161, v161, v93, v94
	v_max_f32_e32 v161, v161, v95
	v_mov_b32_e32 v163, v161
	s_nop 1
	v_permlane32_swap_b32_e32 v161, v163
	v_max_f32_e32 v161, v161, v163
	v_sub_f32_e32 v163, v161, v162
	v_cmp_ge_f32_e32 vcc, s19, v163
	s_cmp_eq_u64 vcc, exec
	s_cbranch_scc0 .Lw1slow_g0a
	v_sub_f32_e32 v64, v64, v162
	v_exp_f32_e32 v64, v64
	v_sub_f32_e32 v65, v65, v162
	v_exp_f32_e32 v65, v65
	v_sub_f32_e32 v66, v66, v162
	v_exp_f32_e32 v66, v66
	v_add_f32_e32 v188, v65, v64
	v_sub_f32_e32 v67, v67, v162
	v_exp_f32_e32 v67, v67
	v_add_f32_e32 v188, v66, v188
	v_sub_f32_e32 v68, v68, v162
	v_exp_f32_e32 v68, v68
	v_add_f32_e32 v188, v67, v188
	v_sub_f32_e32 v69, v69, v162
	v_exp_f32_e32 v69, v69
	v_add_f32_e32 v188, v68, v188
	v_sub_f32_e32 v70, v70, v162
	v_exp_f32_e32 v70, v70
	v_add_f32_e32 v188, v69, v188
	v_sub_f32_e32 v71, v71, v162
	v_exp_f32_e32 v71, v71
	v_add_f32_e32 v188, v70, v188
	v_sub_f32_e32 v72, v72, v162
	v_exp_f32_e32 v72, v72
	v_add_f32_e32 v188, v71, v188
	v_sub_f32_e32 v73, v73, v162
	v_exp_f32_e32 v73, v73
	v_add_f32_e32 v188, v72, v188
	v_sub_f32_e32 v74, v74, v162
	v_exp_f32_e32 v74, v74
	v_add_f32_e32 v188, v73, v188
	v_sub_f32_e32 v75, v75, v162
	v_exp_f32_e32 v75, v75
	v_add_f32_e32 v188, v74, v188
	v_sub_f32_e32 v76, v76, v162
	v_exp_f32_e32 v76, v76
	v_add_f32_e32 v188, v75, v188
	v_sub_f32_e32 v77, v77, v162
	v_exp_f32_e32 v77, v77
	v_add_f32_e32 v188, v76, v188
	v_sub_f32_e32 v78, v78, v162
	v_exp_f32_e32 v78, v78
	v_add_f32_e32 v188, v77, v188
	v_sub_f32_e32 v79, v79, v162
	v_exp_f32_e32 v79, v79
	v_add_f32_e32 v188, v78, v188
	v_sub_f32_e32 v80, v80, v162
	v_exp_f32_e32 v80, v80
	v_add_f32_e32 v188, v79, v188
	v_sub_f32_e32 v81, v81, v162
	v_exp_f32_e32 v81, v81
	v_add_f32_e32 v188, v80, v188
	v_sub_f32_e32 v82, v82, v162
	v_exp_f32_e32 v82, v82
	v_add_f32_e32 v188, v81, v188
	v_sub_f32_e32 v83, v83, v162
	v_exp_f32_e32 v83, v83
	v_add_f32_e32 v188, v82, v188
	v_sub_f32_e32 v84, v84, v162
	v_exp_f32_e32 v84, v84
	v_add_f32_e32 v188, v83, v188
	v_sub_f32_e32 v85, v85, v162
	v_exp_f32_e32 v85, v85
	v_add_f32_e32 v188, v84, v188
	v_sub_f32_e32 v86, v86, v162
	v_exp_f32_e32 v86, v86
	v_add_f32_e32 v188, v85, v188
	v_sub_f32_e32 v87, v87, v162
	v_exp_f32_e32 v87, v87
	v_add_f32_e32 v188, v86, v188
	v_sub_f32_e32 v88, v88, v162
	v_exp_f32_e32 v88, v88
	v_add_f32_e32 v188, v87, v188
	v_sub_f32_e32 v89, v89, v162
	v_exp_f32_e32 v89, v89
	v_add_f32_e32 v188, v88, v188
	v_sub_f32_e32 v90, v90, v162
	v_exp_f32_e32 v90, v90
	v_add_f32_e32 v188, v89, v188
	v_sub_f32_e32 v91, v91, v162
	v_exp_f32_e32 v91, v91
	v_add_f32_e32 v188, v90, v188
	v_sub_f32_e32 v92, v92, v162
	v_exp_f32_e32 v92, v92
	v_add_f32_e32 v188, v91, v188
	v_sub_f32_e32 v93, v93, v162
	v_exp_f32_e32 v93, v93
	v_add_f32_e32 v188, v92, v188
	v_sub_f32_e32 v94, v94, v162
	v_exp_f32_e32 v94, v94
	v_add_f32_e32 v188, v93, v188
	v_sub_f32_e32 v95, v95, v162
	v_exp_f32_e32 v95, v95
	v_add_f32_e32 v188, v94, v188
	v_add_f32_e32 v188, v95, v188
	v_mov_b32_e32 v189, v188
	v_cvt_pk_bf16_f32 v64, v64, v65
	v_cvt_pk_bf16_f32 v65, v66, v67
	v_cvt_pk_bf16_f32 v66, v68, v69
	v_cvt_pk_bf16_f32 v67, v70, v71
	v_cvt_pk_bf16_f32 v68, v72, v73
	v_cvt_pk_bf16_f32 v69, v74, v75
	v_cvt_pk_bf16_f32 v70, v76, v77
	v_cvt_pk_bf16_f32 v71, v78, v79
	v_cvt_pk_bf16_f32 v72, v80, v81
	v_cvt_pk_bf16_f32 v73, v82, v83
	v_cvt_pk_bf16_f32 v74, v84, v85
	v_cvt_pk_bf16_f32 v75, v86, v87
	v_cvt_pk_bf16_f32 v76, v88, v89
	v_cvt_pk_bf16_f32 v77, v90, v91
	v_cvt_pk_bf16_f32 v78, v92, v93
	v_cvt_pk_bf16_f32 v79, v94, v95
	v_permlane32_swap_b32_e32 v188, v189
	v_add_f32_e32 v156, v156, v188
	v_add_f32_e32 v156, v156, v189
; #define VRDK(L, H, KS) do { _Pragma("unroll") for (int d0 = 0; d0 < 4; ++d0) { L[d0] = vtr(vp + v_rd_off(d0, KS, 0)); H[d0] = vtr(vp + v_rd_off(d0, KS, 1)); } } while (0)
; #define PVK(pa, L, H) do { _Pragma("unroll") for (int d0 = 0; d0 < 4; ++d0) o[d0] = __builtin_amdgcn_mfma_f32_32x32x16_bf16(pa, PK(L[d0], H[d0]), o[d0], 0, 0, 0); } while (0)
; template <int NQ, bool QREG> __device__ __forceinline__ void qkt(f32x16& p0, f32x16& p1, const bf16_t* Ks, const bf16x8* qr, const bf16_t* Qw, int r32, int hi, int qcolB) {
;   p0 = f32x16{}; p1 = f32x16{};
; #pragma unroll
;   for (int d0 = 0; d0 < NQ; ++d0) { int cb = qcolB + (d0 * 16 + hi * 8) * 2;
;     bf16x8 b0 = *reinterpret_cast<const bf16x8*>((const char*)Ks + KSWZ(r32, cb));
;     bf16x8 b1 = *reinterpret_cast<const bf16x8*>((const char*)Ks + KSWZ(32 + r32, cb));
;     const bf16x8 qv = QREG ? qr[d0] : ld8(Qw + d0 * 16);
;     p0 = __builtin_amdgcn_mfma_f32_32x32x16_bf16(b0, qv, p0, 0, 0, 0); p1 = __builtin_amdgcn_mfma_f32_32x32x16_bf16(b1, qv, p1, 0, 0, 0); }
;   if (QREG) { __builtin_amdgcn_sched_group_barrier(0x100, 2 * NQ, 0); __builtin_amdgcn_sched_group_barrier(0x008, 2 * NQ, 0); }
; }
; template <bool PIPE> __device__ __forceinline__ void pv_d0(f32x16* o, lds_cptr vp, bf16x8 pa0, bf16x8 pa1, bf16x8 pa2, bf16x8 pa3) {
;   s16x4 La[4], Ha[4], Lb[4], Hb[4];
;   if constexpr (!PIPE) {
;     VRDK(La, Ha, 0); PVK(pa0, La, Ha); VRDK(La, Ha, 1); PVK(pa1, La, Ha); VRDK(La, Ha, 2); PVK(pa2, La, Ha); VRDK(La, Ha, 3); PVK(pa3, La, Ha);
;     return;
;   }
;   VRDK(La, Ha, 0); VRDK(Lb, Hb, 1);
;   PVK(pa0, La, Ha); VRDK(La, Ha, 2);
;   PVK(pa1, Lb, Hb); VRDK(Lb, Hb, 3);
;   PVK(pa2, La, Ha); PVK(pa3, Lb, Hb);
;   __builtin_amdgcn_sched_group_barrier(0x100, 16, 0); __builtin_amdgcn_sched_group_barrier(0x008, 4, 0);
;   __builtin_amdgcn_sched_group_barrier(0x100, 8, 0);  __builtin_amdgcn_sched_group_barrier(0x008, 4, 0);
;   __builtin_amdgcn_sched_group_barrier(0x100, 8, 0);  __builtin_amdgcn_sched_group_barrier(0x008, 8, 0);
; }
.Lw1join_g0a:
	s_waitcnt lgkmcnt(0)
	s_barrier
	s_lshl_b32 s9, s8, 14
	s_add_i32 s11, s9, 0
	s_setprio 1
	v_add_u32_e32 v165, s10, v214
	ds_read_b64_tr_b16 v[80:81], v165
	ds_read_b64_tr_b16 v[82:83], v165 offset:2048
	ds_read_b64_tr_b16 v[84:85], v165 offset:512
	ds_read_b64_tr_b16 v[86:87], v165 offset:2560
	ds_read_b64_tr_b16 v[88:89], v165 offset:1024
	ds_read_b64_tr_b16 v[90:91], v165 offset:3072
	ds_read_b64_tr_b16 v[92:93], v165 offset:1536
	ds_read_b64_tr_b16 v[94:95], v165 offset:3584
	ds_read_b64_tr_b16 v[166:167], v165 offset:4096
	ds_read_b64_tr_b16 v[168:169], v165 offset:6144
	ds_read_b64_tr_b16 v[170:171], v165 offset:4608
	ds_read_b64_tr_b16 v[172:173], v165 offset:6656
	ds_read_b64_tr_b16 v[174:175], v165 offset:5120
	ds_read_b64_tr_b16 v[176:177], v165 offset:7168
	ds_read_b64_tr_b16 v[188:189], v165 offset:5632
	ds_read_b64_tr_b16 v[190:191], v165 offset:7680
	s_waitcnt lgkmcnt(14)
	v_mfma_f32_32x32x16_bf16 v[32:47], v[64:67], v[80:83], v[32:47]
	s_waitcnt lgkmcnt(12)
	v_mfma_f32_32x32x16_bf16 v[48:63], v[64:67], v[84:87], v[48:63]
	s_waitcnt lgkmcnt(10)
	v_mfma_f32_32x32x16_bf16 v[16:31], v[64:67], v[88:91], v[16:31]
	s_waitcnt lgkmcnt(8)
	v_mfma_f32_32x32x16_bf16 v[0:15], v[64:67], v[92:95], v[0:15]
	ds_read_b64_tr_b16 v[64:65], v165 offset:8192
	ds_read_b64_tr_b16 v[66:67], v165 offset:10240
	ds_read_b64_tr_b16 v[80:81], v165 offset:8704
	ds_read_b64_tr_b16 v[82:83], v165 offset:10752
	ds_read_b64_tr_b16 v[84:85], v165 offset:9216
	ds_read_b64_tr_b16 v[86:87], v165 offset:11264
	ds_read_b64_tr_b16 v[88:89], v165 offset:9728
	ds_read_b64_tr_b16 v[90:91], v165 offset:11776
	s_waitcnt lgkmcnt(14)
	v_mfma_f32_32x32x16_bf16 v[32:47], v[68:71], v[166:169], v[32:47]
	s_waitcnt lgkmcnt(12)
	v_mfma_f32_32x32x16_bf16 v[48:63], v[68:71], v[170:173], v[48:63]
	s_waitcnt lgkmcnt(10)
	v_mfma_f32_32x32x16_bf16 v[16:31], v[68:71], v[174:177], v[16:31]
	s_waitcnt lgkmcnt(8)
	v_mfma_f32_32x32x16_bf16 v[0:15], v[68:71], v[188:191], v[0:15]
	ds_read_b64_tr_b16 v[68:69], v165 offset:12288
	ds_read_b64_tr_b16 v[70:71], v165 offset:14336
	ds_read_b64_tr_b16 v[92:93], v165 offset:12800
	ds_read_b64_tr_b16 v[94:95], v165 offset:14848
	ds_read_b64_tr_b16 v[166:167], v165 offset:13312
	ds_read_b64_tr_b16 v[168:169], v165 offset:15360
	ds_read_b64_tr_b16 v[170:171], v165 offset:13824
	ds_read_b64_tr_b16 v[172:173], v165 offset:15872
	s_waitcnt lgkmcnt(14)
	v_mfma_f32_32x32x16_bf16 v[32:47], v[72:75], v[64:67], v[32:47]
	s_waitcnt lgkmcnt(12)
	v_mfma_f32_32x32x16_bf16 v[48:63], v[72:75], v[80:83], v[48:63]
	s_waitcnt lgkmcnt(10)
	v_mfma_f32_32x32x16_bf16 v[16:31], v[72:75], v[84:87], v[16:31]
	s_waitcnt lgkmcnt(8)
	v_mfma_f32_32x32x16_bf16 v[0:15], v[72:75], v[88:91], v[0:15]
	s_waitcnt lgkmcnt(6)
	v_mfma_f32_32x32x16_bf16 v[32:47], v[76:79], v[68:71], v[32:47]
	s_waitcnt lgkmcnt(4)
	v_mfma_f32_32x32x16_bf16 v[48:63], v[76:79], v[92:95], v[48:63]
	s_waitcnt lgkmcnt(2)
	v_mfma_f32_32x32x16_bf16 v[16:31], v[76:79], v[166:169], v[16:31]
	s_waitcnt lgkmcnt(0)
	v_mfma_f32_32x32x16_bf16 v[0:15], v[76:79], v[170:173], v[0:15]
	v_add_u32_e32 v68, s11, v157
	ds_read_b128 v[80:83], v68 offset:57344
	v_add_u32_e32 v165, s11, v158
	ds_read_b128 v[64:67], v68 offset:49152
	ds_read_b128 v[170:173], v165 offset:57344
	ds_read_b128 v[166:169], v165 offset:49152
	v_add_u32_e32 v165, s11, v159
	s_waitcnt lgkmcnt(3)
	v_mfma_f32_32x32x16_bf16 v[80:95], v[80:83], v[104:107], 0
	s_waitcnt lgkmcnt(1)
	v_mfma_f32_32x32x16_bf16 v[80:95], v[170:173], v[108:111], v[80:95]
	ds_read_b128 v[170:173], v165 offset:57344
	v_mfma_f32_32x32x16_bf16 v[64:79], v[64:67], v[104:107], 0
	s_waitcnt lgkmcnt(1)
	v_mfma_f32_32x32x16_bf16 v[64:79], v[166:169], v[108:111], v[64:79]
	ds_read_b128 v[166:169], v165 offset:49152
	v_add_u32_e32 v165, s11, v160
	s_waitcnt lgkmcnt(1)
	v_mfma_f32_32x32x16_bf16 v[80:95], v[170:173], v[112:115], v[80:95]
	ds_read_b128 v[170:173], v165 offset:57344
	s_waitcnt lgkmcnt(1)
	v_mfma_f32_32x32x16_bf16 v[64:79], v[166:169], v[112:115], v[64:79]
	ds_read_b128 v[166:169], v165 offset:49152
	s_waitcnt lgkmcnt(0)
	v_mfma_f32_32x32x16_bf16 v[64:79], v[166:169], v[100:103], v[64:79]
	v_mfma_f32_32x32x16_bf16 v[80:95], v[170:173], v[100:103], v[80:95]
	s_setprio 0
	s_add_i32 s10, s7, 2
	s_cmp_ge_u32 s10, s83
	s_cselect_b64 s[34:35], -1, 0
	s_and_b64 vcc, exec, s[34:35]
	s_cbranch_vccnz .LBB0_368
	s_lshl_b32 s11, s5, 14
	s_add_i32 s11, s11, 0
	v_add_u32_e32 v165, s11, v183
	v_add_u32_e32 v166, s11, v210
	v_add_u32_e32 v167, s11, v211
	v_add_u32_e32 v168, s11, v212
	s_waitcnt vmcnt(3)
	ds_write_b128 v165, v[132:135]
	s_waitcnt vmcnt(1)
	ds_write_b128 v166, v[136:139]
	s_waitcnt vmcnt(1)
	ds_write_b128 v167, v[140:143] offset:49152
	s_waitcnt vmcnt(0)
	ds_write_b128 v168, v[144:147] offset:49152

; __device__ __forceinline__ void partialSM(f32x16& p0, f32x16& p1, float& m_reg, float& alpha) {
;   constexpr float THR2 = THR * 1.4426950408889634f;
;   float pmax = p0[0];
; #pragma unroll
;   for (int r = 1; r < 16; ++r) pmax = fmaxf(pmax, p0[r]);
; #pragma unroll
;   for (int r = 0; r < 16; ++r) pmax = fmaxf(pmax, p1[r]);
;   { auto rr = __builtin_amdgcn_permlane32_swap(__float_as_uint(pmax), __float_as_uint(pmax), false, false);
;     pmax = fmaxf(__uint_as_float(rr[0]), __uint_as_float(rr[1])); }
;   float mn;
;   if (__builtin_expect(__all(pmax - m_reg <= THR2), 1)) { mn = m_reg; alpha = 1.f; }
;   else { mn = fmaxf(m_reg, pmax); alpha = __builtin_amdgcn_exp2f(m_reg - mn); m_reg = mn; }
; #pragma unroll
;   for (int r = 0; r < 16; ++r) { p0[r] -= mn; p1[r] -= mn; }
; #pragma unroll
;   for (int r = 0; r < 16; ++r) p0[r] = __builtin_amdgcn_exp2f(p0[r]);
; }
; __device__ __forceinline__ void finishSM(f32x16& p0, f32x16& p1, float alpha, float& l_reg, bf16x8& pa0, bf16x8& pa1, bf16x8& pa2, bf16x8& pa3) {
; #pragma unroll
;   for (int r = 0; r < 16; ++r) p1[r] = __builtin_amdgcn_exp2f(p1[r]);
;   float ps = 0;
; #pragma unroll
;   for (int r = 0; r < 16; ++r) ps += p0[r];
; #pragma unroll
;   for (int r = 0; r < 16; ++r) ps += p1[r];
;   { auto rr = __builtin_amdgcn_permlane32_swap(__float_as_uint(ps), __float_as_uint(ps), false, false);
;     ps = __uint_as_float(rr[0]) + __uint_as_float(rr[1]); }
;   l_reg = l_reg * alpha + ps;
;     ...
;   PK4(p0, 0, pa0); PK4(p0, 8, pa1); PK4(p1, 0, pa2); PK4(p1, 8, pa3);
;     ...
; }
.LBB0_370:
	s_nop 1
	v_max3_f32 v152, v64, v65, v66
	v_max3_f32 v152, v152, v67, v68
	v_max3_f32 v152, v152, v69, v70
	v_max3_f32 v152, v152, v71, v72
	v_max3_f32 v152, v152, v73, v74
	v_max3_f32 v152, v152, v75, v76
	v_max3_f32 v152, v152, v77, v78
	v_max3_f32 v152, v152, v79, v80
	v_max3_f32 v152, v152, v81, v82
	v_max3_f32 v152, v152, v83, v84
	v_max3_f32 v152, v152, v85, v86
	v_max3_f32 v152, v152, v87, v88
	v_max3_f32 v152, v152, v89, v90
	v_max3_f32 v152, v152, v91, v92
	v_max3_f32 v152, v152, v93, v94
	v_max_f32_e32 v152, v152, v95
	v_mov_b32_e32 v153, v152
	s_nop 1
	v_permlane32_swap_b32_e32 v152, v153
	v_max_f32_e32 v152, v152, v153
	v_sub_f32_e32 v153, v152, v162
	v_cmp_ge_f32_e32 vcc, s19, v153
	s_cmp_eq_u64 vcc, exec
	s_cbranch_scc0 .Lw1slow_g0b
	v_sub_f32_e32 v64, v64, v162
	v_exp_f32_e32 v64, v64
	v_sub_f32_e32 v65, v65, v162
	v_exp_f32_e32 v65, v65
	v_sub_f32_e32 v66, v66, v162
	v_exp_f32_e32 v66, v66
	v_add_f32_e32 v190, v65, v64
	v_sub_f32_e32 v67, v67, v162
	v_exp_f32_e32 v67, v67
	v_add_f32_e32 v190, v66, v190
	v_sub_f32_e32 v68, v68, v162
	v_exp_f32_e32 v68, v68
	v_add_f32_e32 v190, v67, v190
	v_sub_f32_e32 v69, v69, v162
	v_exp_f32_e32 v69, v69
	v_add_f32_e32 v190, v68, v190
	v_sub_f32_e32 v70, v70, v162
	v_exp_f32_e32 v70, v70
	v_add_f32_e32 v190, v69, v190
	v_sub_f32_e32 v71, v71, v162
	v_exp_f32_e32 v71, v71
	v_add_f32_e32 v190, v70, v190
	v_sub_f32_e32 v72, v72, v162
	v_exp_f32_e32 v72, v72
	v_add_f32_e32 v190, v71, v190
	v_sub_f32_e32 v73, v73, v162
	v_exp_f32_e32 v73, v73
	v_add_f32_e32 v190, v72, v190
	v_sub_f32_e32 v74, v74, v162
	v_exp_f32_e32 v74, v74
	v_add_f32_e32 v190, v73, v190
	v_sub_f32_e32 v75, v75, v162
	v_exp_f32_e32 v75, v75
	v_add_f32_e32 v190, v74, v190
	v_sub_f32_e32 v76, v76, v162
	v_exp_f32_e32 v153, v76
	v_add_f32_e32 v190, v75, v190
	v_sub_f32_e32 v77, v77, v162
	v_exp_f32_e32 v154, v77
	v_add_f32_e32 v190, v153, v190
	v_sub_f32_e32 v78, v78, v162
	v_exp_f32_e32 v155, v78
	v_add_f32_e32 v190, v154, v190
	v_sub_f32_e32 v79, v79, v162
	v_exp_f32_e32 v165, v79
	v_add_f32_e32 v190, v155, v190
	v_sub_f32_e32 v80, v80, v162
	v_exp_f32_e32 v80, v80
	v_add_f32_e32 v190, v165, v190
	v_sub_f32_e32 v81, v81, v162
	v_exp_f32_e32 v81, v81
	v_add_f32_e32 v190, v80, v190
	v_sub_f32_e32 v82, v82, v162
	v_exp_f32_e32 v82, v82
	v_add_f32_e32 v190, v81, v190
	v_sub_f32_e32 v83, v83, v162
	v_exp_f32_e32 v83, v83
	v_add_f32_e32 v190, v82, v190
	v_sub_f32_e32 v84, v84, v162
	v_exp_f32_e32 v84, v84
	v_add_f32_e32 v190, v83, v190
	v_sub_f32_e32 v85, v85, v162
	v_exp_f32_e32 v85, v85
	v_add_f32_e32 v190, v84, v190
	v_sub_f32_e32 v86, v86, v162
	v_exp_f32_e32 v86, v86
	v_add_f32_e32 v190, v85, v190
	v_sub_f32_e32 v87, v87, v162
	v_exp_f32_e32 v87, v87
	v_add_f32_e32 v190, v86, v190
	v_sub_f32_e32 v88, v88, v162
	v_exp_f32_e32 v88, v88
	v_add_f32_e32 v190, v87, v190
	v_sub_f32_e32 v89, v89, v162
	v_exp_f32_e32 v89, v89
	v_add_f32_e32 v190, v88, v190
	v_sub_f32_e32 v90, v90, v162
	v_exp_f32_e32 v90, v90
	v_add_f32_e32 v190, v89, v190
	v_sub_f32_e32 v91, v91, v162
	v_exp_f32_e32 v91, v91
	v_add_f32_e32 v190, v90, v190
	v_sub_f32_e32 v92, v92, v162
	v_exp_f32_e32 v92, v92
	v_add_f32_e32 v190, v91, v190
	v_sub_f32_e32 v93, v93, v162
	v_exp_f32_e32 v93, v93
	v_add_f32_e32 v190, v92, v190
	v_sub_f32_e32 v94, v94, v162
	v_exp_f32_e32 v94, v94
	v_add_f32_e32 v190, v93, v190
	v_sub_f32_e32 v95, v95, v162
	v_exp_f32_e32 v95, v95
	v_add_f32_e32 v190, v94, v190
	v_add_f32_e32 v190, v95, v190
	v_mov_b32_e32 v191, v190
	v_cvt_pk_bf16_f32 v76, v64, v65
	v_cvt_pk_bf16_f32 v77, v66, v67
	v_cvt_pk_bf16_f32 v78, v68, v69
	v_cvt_pk_bf16_f32 v79, v70, v71
	v_cvt_pk_bf16_f32 v72, v72, v73
	v_cvt_pk_bf16_f32 v73, v74, v75
	v_cvt_pk_bf16_f32 v74, v153, v154
	v_cvt_pk_bf16_f32 v75, v155, v165
	v_cvt_pk_bf16_f32 v68, v80, v81
	v_cvt_pk_bf16_f32 v69, v82, v83
	v_cvt_pk_bf16_f32 v70, v84, v85
	v_cvt_pk_bf16_f32 v71, v86, v87
	v_cvt_pk_bf16_f32 v64, v88, v89
	v_cvt_pk_bf16_f32 v65, v90, v91
	v_cvt_pk_bf16_f32 v66, v92, v93
	v_cvt_pk_bf16_f32 v67, v94, v95
	v_permlane32_swap_b32_e32 v190, v191
	v_add_f32_e32 v156, v156, v190
	v_add_f32_e32 v156, v156, v191
.Lw1join_g0b:
	s_waitcnt lgkmcnt(0)
	s_barrier
	s_add_u32 s0, s0, 0x240000
	s_addc_u32 s1, s1, 0
	s_and_b64 vcc, exec, s[34:35]
	s_cbranch_vccnz .LBB0_376
	s_mov_b32 s9, s8
	s_mov_b32 s8, s6
	s_mov_b32 s7, s10
	s_branch .LBB0_356
; __device__ __forceinline__ void partialSM(f32x16& p0, f32x16& p1, float& m_reg, float& alpha) {
;   constexpr float THR2 = THR * 1.4426950408889634f;
;   float pmax = p0[0];
; #pragma unroll
;   for (int r = 1; r < 16; ++r) pmax = fmaxf(pmax, p0[r]);
; #pragma unroll
;   for (int r = 0; r < 16; ++r) pmax = fmaxf(pmax, p1[r]);
;   { auto rr = __builtin_amdgcn_permlane32_swap(__float_as_uint(pmax), __float_as_uint(pmax), false, false);
;     pmax = fmaxf(__uint_as_float(rr[0]), __uint_as_float(rr[1])); }
;   float mn;
;   if (__builtin_expect(__all(pmax - m_reg <= THR2), 1)) { mn = m_reg; alpha = 1.f; }
;   else { mn = fmaxf(m_reg, pmax); alpha = __builtin_amdgcn_exp2f(m_reg - mn); m_reg = mn; }
; #pragma unroll
;   for (int r = 0; r < 16; ++r) { p0[r] -= mn; p1[r] -= mn; }
; #pragma unroll
;   for (int r = 0; r < 16; ++r) p0[r] = __builtin_amdgcn_exp2f(p0[r]);
; }
; __device__ __forceinline__ void finishSM(f32x16& p0, f32x16& p1, float alpha, float& l_reg, bf16x8& pa0, bf16x8& pa1, bf16x8& pa2, bf16x8& pa3) {
; #pragma unroll
;   for (int r = 0; r < 16; ++r) p1[r] = __builtin_amdgcn_exp2f(p1[r]);
;   float ps = 0;
; #pragma unroll
;   for (int r = 0; r < 16; ++r) ps += p0[r];
; #pragma unroll
;   for (int r = 0; r < 16; ++r) ps += p1[r];
;   { auto rr = __builtin_amdgcn_permlane32_swap(__float_as_uint(ps), __float_as_uint(ps), false, false);
;     ps = __uint_as_float(rr[0]) + __uint_as_float(rr[1]); }
;   l_reg = l_reg * alpha + ps;
;     ...
;   PK4(p0, 0, pa0); PK4(p0, 8, pa1); PK4(p1, 0, pa2); PK4(p1, 8, pa3);
;     ...
; }
.Lw1slow_g1a:
	v_max_f32_e32 v193, v223, v192
	v_sub_f32_e32 v192, v223, v193
	v_exp_f32_e32 v192, v192
	v_mov_b32_e32 v223, v193
	s_and_saveexec_b64 s[72:73], s[38:39]
	ds_write_b32 v213, v192 offset:128
	s_or_b64 exec, exec, s[72:73]
	s_waitcnt lgkmcnt(0)
	v_add_u32_e32 v194, s4, v215
	ds_read_b128 v[226:229], v194 offset:224
	ds_read_b128 v[230:233], v194 offset:192
	ds_read_b128 v[234:237], v194 offset:160
	ds_read_b128 v[238:241], v194 offset:128
	s_waitcnt lgkmcnt(0)
	v_pk_mul_f32 v[44:45], v[44:45], v[226:227]
	v_pk_mul_f32 v[40:41], v[40:41], v[230:231]
	v_pk_mul_f32 v[36:37], v[36:37], v[234:235]
	v_pk_mul_f32 v[46:47], v[46:47], v[228:229]
	v_pk_mul_f32 v[42:43], v[42:43], v[232:233]
	v_pk_mul_f32 v[38:39], v[38:39], v[236:237]
	v_pk_mul_f32 v[34:35], v[34:35], v[240:241]
	v_pk_mul_f32 v[32:33], v[32:33], v[238:239]
	v_pk_mul_f32 v[60:61], v[60:61], v[226:227]
	v_pk_mul_f32 v[56:57], v[56:57], v[230:231]
	v_pk_mul_f32 v[52:53], v[52:53], v[234:235]
	v_pk_mul_f32 v[62:63], v[62:63], v[228:229]
	v_pk_mul_f32 v[58:59], v[58:59], v[232:233]
	v_pk_mul_f32 v[54:55], v[54:55], v[236:237]
	v_pk_mul_f32 v[50:51], v[50:51], v[240:241]
	v_pk_mul_f32 v[48:49], v[48:49], v[238:239]
	v_pk_mul_f32 v[28:29], v[28:29], v[226:227]
	v_pk_mul_f32 v[24:25], v[24:25], v[230:231]
	v_pk_mul_f32 v[20:21], v[20:21], v[234:235]
	v_pk_mul_f32 v[30:31], v[30:31], v[228:229]
	v_pk_mul_f32 v[26:27], v[26:27], v[232:233]
	v_pk_mul_f32 v[22:23], v[22:23], v[236:237]
	v_pk_mul_f32 v[18:19], v[18:19], v[240:241]
	v_pk_mul_f32 v[16:17], v[16:17], v[238:239]
	v_pk_mul_f32 v[12:13], v[12:13], v[226:227]
	v_pk_mul_f32 v[8:9], v[8:9], v[230:231]
	v_pk_mul_f32 v[4:5], v[4:5], v[234:235]
	v_pk_mul_f32 v[14:15], v[14:15], v[228:229]
	v_pk_mul_f32 v[10:11], v[10:11], v[232:233]
	v_pk_mul_f32 v[6:7], v[6:7], v[236:237]
	v_pk_mul_f32 v[2:3], v[2:3], v[240:241]
	v_pk_mul_f32 v[0:1], v[0:1], v[238:239]
	v_mul_f32_e32 v222, v222, v192
	v_sub_f32_e32 v64, v64, v223
	v_exp_f32_e32 v64, v64
	v_sub_f32_e32 v65, v65, v223
	v_exp_f32_e32 v65, v65
	v_sub_f32_e32 v66, v66, v223
	v_exp_f32_e32 v66, v66
	v_add_f32_e32 v225, v65, v64
	v_sub_f32_e32 v67, v67, v223
	v_exp_f32_e32 v67, v67
	v_add_f32_e32 v225, v66, v225
	v_sub_f32_e32 v68, v68, v223
	v_exp_f32_e32 v68, v68
	v_add_f32_e32 v225, v67, v225
	v_sub_f32_e32 v69, v69, v223
	v_exp_f32_e32 v69, v69
	v_add_f32_e32 v225, v68, v225
	v_sub_f32_e32 v70, v70, v223
	v_exp_f32_e32 v70, v70
	v_add_f32_e32 v225, v69, v225
	v_sub_f32_e32 v71, v71, v223
	v_exp_f32_e32 v71, v71
	v_add_f32_e32 v225, v70, v225
	v_sub_f32_e32 v72, v72, v223
	v_exp_f32_e32 v72, v72
	v_add_f32_e32 v225, v71, v225
	v_sub_f32_e32 v73, v73, v223
	v_exp_f32_e32 v73, v73
	v_add_f32_e32 v225, v72, v225
	v_sub_f32_e32 v74, v74, v223
	v_exp_f32_e32 v74, v74
	v_add_f32_e32 v225, v73, v225
	v_sub_f32_e32 v75, v75, v223
	v_exp_f32_e32 v75, v75
	v_add_f32_e32 v225, v74, v225
	v_sub_f32_e32 v76, v76, v223
	v_exp_f32_e32 v192, v76
	v_add_f32_e32 v225, v75, v225
	v_sub_f32_e32 v77, v77, v223
	v_exp_f32_e32 v193, v77
	v_add_f32_e32 v225, v192, v225
	v_sub_f32_e32 v78, v78, v223
	v_exp_f32_e32 v194, v78
	v_add_f32_e32 v225, v193, v225
	v_sub_f32_e32 v79, v79, v223
	v_exp_f32_e32 v195, v79
	v_add_f32_e32 v225, v194, v225
	v_sub_f32_e32 v80, v80, v223
	v_exp_f32_e32 v80, v80
	v_add_f32_e32 v225, v195, v225
	v_sub_f32_e32 v81, v81, v223
	v_exp_f32_e32 v81, v81
	v_add_f32_e32 v225, v80, v225
	v_sub_f32_e32 v82, v82, v223
	v_exp_f32_e32 v82, v82
	v_add_f32_e32 v225, v81, v225
	v_sub_f32_e32 v83, v83, v223
	v_exp_f32_e32 v83, v83
	v_add_f32_e32 v225, v82, v225
	v_sub_f32_e32 v84, v84, v223
	v_exp_f32_e32 v84, v84
	v_add_f32_e32 v225, v83, v225
	v_sub_f32_e32 v85, v85, v223
	v_exp_f32_e32 v85, v85
	v_add_f32_e32 v225, v84, v225
	v_sub_f32_e32 v86, v86, v223
	v_exp_f32_e32 v86, v86
	v_add_f32_e32 v225, v85, v225
	v_sub_f32_e32 v87, v87, v223
	v_exp_f32_e32 v87, v87
	v_add_f32_e32 v225, v86, v225
	v_sub_f32_e32 v88, v88, v223
	v_exp_f32_e32 v88, v88
	v_add_f32_e32 v225, v87, v225
	v_sub_f32_e32 v89, v89, v223
	v_exp_f32_e32 v89, v89
	v_add_f32_e32 v225, v88, v225
	v_sub_f32_e32 v90, v90, v223
	v_exp_f32_e32 v90, v90
	v_add_f32_e32 v225, v89, v225
	v_sub_f32_e32 v91, v91, v223
	v_exp_f32_e32 v91, v91
	v_add_f32_e32 v225, v90, v225
	v_sub_f32_e32 v92, v92, v223
	v_exp_f32_e32 v92, v92
	v_add_f32_e32 v225, v91, v225
	v_sub_f32_e32 v93, v93, v223
	v_exp_f32_e32 v93, v93
	v_add_f32_e32 v225, v92, v225
	v_sub_f32_e32 v94, v94, v223
	v_exp_f32_e32 v94, v94
	v_add_f32_e32 v225, v93, v225
	v_sub_f32_e32 v95, v95, v223
	v_exp_f32_e32 v95, v95
	v_add_f32_e32 v225, v94, v225
	v_add_f32_e32 v225, v95, v225
	v_mov_b32_e32 v226, v225
	v_cvt_pk_bf16_f32 v76, v64, v65
	v_cvt_pk_bf16_f32 v77, v66, v67
	v_cvt_pk_bf16_f32 v78, v68, v69
	v_cvt_pk_bf16_f32 v79, v70, v71
	v_cvt_pk_bf16_f32 v72, v72, v73
	v_cvt_pk_bf16_f32 v73, v74, v75
	v_cvt_pk_bf16_f32 v74, v192, v193
	v_cvt_pk_bf16_f32 v75, v194, v195
	v_cvt_pk_bf16_f32 v68, v80, v81
	v_cvt_pk_bf16_f32 v69, v82, v83
	v_cvt_pk_bf16_f32 v70, v84, v85
	v_cvt_pk_bf16_f32 v71, v86, v87
	v_cvt_pk_bf16_f32 v64, v88, v89
	v_cvt_pk_bf16_f32 v65, v90, v91
	v_cvt_pk_bf16_f32 v66, v92, v93
	v_cvt_pk_bf16_f32 v67, v94, v95
	v_permlane32_swap_b32_e32 v225, v226
	v_add_f32_e32 v222, v222, v225
	v_add_f32_e32 v222, v222, v226
	s_branch .Lw1join_g1a
; __device__ __forceinline__ void partialSM(f32x16& p0, f32x16& p1, float& m_reg, float& alpha) {
;   constexpr float THR2 = THR * 1.4426950408889634f;
;   float pmax = p0[0];
; #pragma unroll
;   for (int r = 1; r < 16; ++r) pmax = fmaxf(pmax, p0[r]);
; #pragma unroll
;   for (int r = 0; r < 16; ++r) pmax = fmaxf(pmax, p1[r]);
;   { auto rr = __builtin_amdgcn_permlane32_swap(__float_as_uint(pmax), __float_as_uint(pmax), false, false);
;     pmax = fmaxf(__uint_as_float(rr[0]), __uint_as_float(rr[1])); }
;   float mn;
;   if (__builtin_expect(__all(pmax - m_reg <= THR2), 1)) { mn = m_reg; alpha = 1.f; }
;   else { mn = fmaxf(m_reg, pmax); alpha = __builtin_amdgcn_exp2f(m_reg - mn); m_reg = mn; }
; #pragma unroll
;   for (int r = 0; r < 16; ++r) { p0[r] -= mn; p1[r] -= mn; }
; #pragma unroll
;   for (int r = 0; r < 16; ++r) p0[r] = __builtin_amdgcn_exp2f(p0[r]);
; }
; __device__ __forceinline__ void finishSM(f32x16& p0, f32x16& p1, float alpha, float& l_reg, bf16x8& pa0, bf16x8& pa1, bf16x8& pa2, bf16x8& pa3) {
; #pragma unroll
;   for (int r = 0; r < 16; ++r) p1[r] = __builtin_amdgcn_exp2f(p1[r]);
;   float ps = 0;
; #pragma unroll
;   for (int r = 0; r < 16; ++r) ps += p0[r];
; #pragma unroll
;   for (int r = 0; r < 16; ++r) ps += p1[r];
;   { auto rr = __builtin_amdgcn_permlane32_swap(__float_as_uint(ps), __float_as_uint(ps), false, false);
;     ps = __uint_as_float(rr[0]) + __uint_as_float(rr[1]); }
;   l_reg = l_reg * alpha + ps;
;     ...
;   PK4(p0, 0, pa0); PK4(p0, 8, pa1); PK4(p1, 0, pa2); PK4(p1, 8, pa3);
;     ...
; }
.Lw1slow_g1b:
	v_max_f32_e32 v228, v223, v227
	v_sub_f32_e32 v227, v223, v228
	v_exp_f32_e32 v227, v227
	v_mov_b32_e32 v223, v228
	s_and_saveexec_b64 s[72:73], s[38:39]
	ds_write_b32 v213, v227 offset:128
	s_or_b64 exec, exec, s[72:73]
	s_waitcnt lgkmcnt(0)
	v_add_u32_e32 v229, s4, v215
	ds_read_b128 v[230:233], v229 offset:224
	ds_read_b128 v[234:237], v229 offset:192
	ds_read_b128 v[238:241], v229 offset:160
	ds_read_b128 v[242:245], v229 offset:128
	s_waitcnt lgkmcnt(0)
	v_pk_mul_f32 v[44:45], v[44:45], v[230:231]
	v_pk_mul_f32 v[40:41], v[40:41], v[234:235]
	v_pk_mul_f32 v[36:37], v[36:37], v[238:239]
	v_pk_mul_f32 v[46:47], v[46:47], v[232:233]
	v_pk_mul_f32 v[42:43], v[42:43], v[236:237]
	v_pk_mul_f32 v[38:39], v[38:39], v[240:241]
	v_pk_mul_f32 v[34:35], v[34:35], v[244:245]
	v_pk_mul_f32 v[32:33], v[32:33], v[242:243]
	v_pk_mul_f32 v[60:61], v[60:61], v[230:231]
	v_pk_mul_f32 v[56:57], v[56:57], v[234:235]
	v_pk_mul_f32 v[52:53], v[52:53], v[238:239]
	v_pk_mul_f32 v[62:63], v[62:63], v[232:233]
	v_pk_mul_f32 v[58:59], v[58:59], v[236:237]
	v_pk_mul_f32 v[54:55], v[54:55], v[240:241]
	v_pk_mul_f32 v[50:51], v[50:51], v[244:245]
	v_pk_mul_f32 v[48:49], v[48:49], v[242:243]
	v_pk_mul_f32 v[28:29], v[28:29], v[230:231]
	v_pk_mul_f32 v[24:25], v[24:25], v[234:235]
	v_pk_mul_f32 v[20:21], v[20:21], v[238:239]
	v_pk_mul_f32 v[30:31], v[30:31], v[232:233]
	v_pk_mul_f32 v[26:27], v[26:27], v[236:237]
	v_pk_mul_f32 v[22:23], v[22:23], v[240:241]
	v_pk_mul_f32 v[18:19], v[18:19], v[244:245]
	v_pk_mul_f32 v[16:17], v[16:17], v[242:243]
	v_pk_mul_f32 v[12:13], v[12:13], v[230:231]
	v_pk_mul_f32 v[8:9], v[8:9], v[234:235]
	v_pk_mul_f32 v[4:5], v[4:5], v[238:239]
	v_pk_mul_f32 v[14:15], v[14:15], v[232:233]
	v_pk_mul_f32 v[10:11], v[10:11], v[236:237]
	v_pk_mul_f32 v[6:7], v[6:7], v[240:241]
	v_pk_mul_f32 v[2:3], v[2:3], v[244:245]
	v_pk_mul_f32 v[0:1], v[0:1], v[242:243]
	v_mul_f32_e32 v222, v222, v227
	v_sub_f32_e32 v64, v64, v223
	v_exp_f32_e32 v64, v64
	v_sub_f32_e32 v65, v65, v223
	v_exp_f32_e32 v65, v65
	v_sub_f32_e32 v66, v66, v223
	v_exp_f32_e32 v66, v66
	v_add_f32_e32 v246, v65, v64
	v_sub_f32_e32 v67, v67, v223
	v_exp_f32_e32 v67, v67
	v_add_f32_e32 v246, v66, v246
	v_sub_f32_e32 v68, v68, v223
	v_exp_f32_e32 v68, v68
	v_add_f32_e32 v246, v67, v246
	v_sub_f32_e32 v69, v69, v223
	v_exp_f32_e32 v69, v69
	v_add_f32_e32 v246, v68, v246
	v_sub_f32_e32 v70, v70, v223
	v_exp_f32_e32 v70, v70
	v_add_f32_e32 v246, v69, v246
	v_sub_f32_e32 v71, v71, v223
	v_exp_f32_e32 v71, v71
	v_add_f32_e32 v246, v70, v246
	v_sub_f32_e32 v72, v72, v223
	v_exp_f32_e32 v72, v72
	v_add_f32_e32 v246, v71, v246
	v_sub_f32_e32 v73, v73, v223
	v_exp_f32_e32 v73, v73
	v_add_f32_e32 v246, v72, v246
	v_sub_f32_e32 v74, v74, v223
	v_exp_f32_e32 v74, v74
	v_add_f32_e32 v246, v73, v246
	v_sub_f32_e32 v75, v75, v223
	v_exp_f32_e32 v75, v75
	v_add_f32_e32 v246, v74, v246
	v_sub_f32_e32 v76, v76, v223
	v_exp_f32_e32 v228, v76
	v_add_f32_e32 v246, v75, v246
	v_sub_f32_e32 v77, v77, v223
	v_exp_f32_e32 v229, v77
	v_add_f32_e32 v246, v228, v246
	v_sub_f32_e32 v78, v78, v223
	v_exp_f32_e32 v230, v78
	v_add_f32_e32 v246, v229, v246
	v_sub_f32_e32 v79, v79, v223
	v_exp_f32_e32 v231, v79
	v_add_f32_e32 v246, v230, v246
	v_sub_f32_e32 v80, v80, v223
	v_exp_f32_e32 v80, v80
	v_add_f32_e32 v246, v231, v246
	v_sub_f32_e32 v81, v81, v223
	v_exp_f32_e32 v81, v81
	v_add_f32_e32 v246, v80, v246
	v_sub_f32_e32 v82, v82, v223
	v_exp_f32_e32 v82, v82
	v_add_f32_e32 v246, v81, v246
	v_sub_f32_e32 v83, v83, v223
	v_exp_f32_e32 v83, v83
	v_add_f32_e32 v246, v82, v246
	v_sub_f32_e32 v84, v84, v223
	v_exp_f32_e32 v84, v84
	v_add_f32_e32 v246, v83, v246
	v_sub_f32_e32 v85, v85, v223
	v_exp_f32_e32 v85, v85
	v_add_f32_e32 v246, v84, v246
	v_sub_f32_e32 v86, v86, v223
	v_exp_f32_e32 v86, v86
	v_add_f32_e32 v246, v85, v246
	v_sub_f32_e32 v87, v87, v223
	v_exp_f32_e32 v87, v87
	v_add_f32_e32 v246, v86, v246
	v_sub_f32_e32 v88, v88, v223
	v_exp_f32_e32 v88, v88
	v_add_f32_e32 v246, v87, v246
	v_sub_f32_e32 v89, v89, v223
	v_exp_f32_e32 v89, v89
	v_add_f32_e32 v246, v88, v246
	v_sub_f32_e32 v90, v90, v223
	v_exp_f32_e32 v90, v90
	v_add_f32_e32 v246, v89, v246
	v_sub_f32_e32 v91, v91, v223
	v_exp_f32_e32 v91, v91
	v_add_f32_e32 v246, v90, v246
	v_sub_f32_e32 v92, v92, v223
	v_exp_f32_e32 v92, v92
	v_add_f32_e32 v246, v91, v246
	v_sub_f32_e32 v93, v93, v223
	v_exp_f32_e32 v93, v93
	v_add_f32_e32 v246, v92, v246
	v_sub_f32_e32 v94, v94, v223
	v_exp_f32_e32 v94, v94
	v_add_f32_e32 v246, v93, v246
	v_sub_f32_e32 v95, v95, v223
	v_exp_f32_e32 v95, v95
	v_add_f32_e32 v246, v94, v246
	v_add_f32_e32 v246, v95, v246
	v_mov_b32_e32 v247, v246
	v_cvt_pk_bf16_f32 v76, v64, v65
	v_cvt_pk_bf16_f32 v77, v66, v67
	v_cvt_pk_bf16_f32 v78, v68, v69
	v_cvt_pk_bf16_f32 v79, v70, v71
	v_cvt_pk_bf16_f32 v72, v72, v73
	v_cvt_pk_bf16_f32 v73, v74, v75
	v_cvt_pk_bf16_f32 v74, v228, v229
	v_cvt_pk_bf16_f32 v75, v230, v231
	v_cvt_pk_bf16_f32 v68, v80, v81
	v_cvt_pk_bf16_f32 v69, v82, v83
	v_cvt_pk_bf16_f32 v70, v84, v85
	v_cvt_pk_bf16_f32 v71, v86, v87
	v_cvt_pk_bf16_f32 v64, v88, v89
	v_cvt_pk_bf16_f32 v65, v90, v91
	v_cvt_pk_bf16_f32 v66, v92, v93
	v_cvt_pk_bf16_f32 v67, v94, v95
	v_permlane32_swap_b32_e32 v246, v247
	v_add_f32_e32 v222, v222, v246
	v_add_f32_e32 v222, v222, v247
	s_branch .Lw1join_g1b
; __device__ __forceinline__ void partialSM(f32x16& p0, f32x16& p1, float& m_reg, float& alpha) {
;   constexpr float THR2 = THR * 1.4426950408889634f;
;   float pmax = p0[0];
; #pragma unroll
;   for (int r = 1; r < 16; ++r) pmax = fmaxf(pmax, p0[r]);
; #pragma unroll
;   for (int r = 0; r < 16; ++r) pmax = fmaxf(pmax, p1[r]);
;   { auto rr = __builtin_amdgcn_permlane32_swap(__float_as_uint(pmax), __float_as_uint(pmax), false, false);
;     pmax = fmaxf(__uint_as_float(rr[0]), __uint_as_float(rr[1])); }
;   float mn;
;   if (__builtin_expect(__all(pmax - m_reg <= THR2), 1)) { mn = m_reg; alpha = 1.f; }
;   else { mn = fmaxf(m_reg, pmax); alpha = __builtin_amdgcn_exp2f(m_reg - mn); m_reg = mn; }
; #pragma unroll
;   for (int r = 0; r < 16; ++r) { p0[r] -= mn; p1[r] -= mn; }
; #pragma unroll
;   for (int r = 0; r < 16; ++r) p0[r] = __builtin_amdgcn_exp2f(p0[r]);
; }
; __device__ __forceinline__ void finishSM(f32x16& p0, f32x16& p1, float alpha, float& l_reg, bf16x8& pa0, bf16x8& pa1, bf16x8& pa2, bf16x8& pa3) {
; #pragma unroll
;   for (int r = 0; r < 16; ++r) p1[r] = __builtin_amdgcn_exp2f(p1[r]);
;   float ps = 0;
; #pragma unroll
;   for (int r = 0; r < 16; ++r) ps += p0[r];
; #pragma unroll
;   for (int r = 0; r < 16; ++r) ps += p1[r];
;   { auto rr = __builtin_amdgcn_permlane32_swap(__float_as_uint(ps), __float_as_uint(ps), false, false);
;     ps = __uint_as_float(rr[0]) + __uint_as_float(rr[1]); }
;   l_reg = l_reg * alpha + ps;
;     ...
;   PK4(p0, 0, pa0); PK4(p0, 8, pa1); PK4(p1, 0, pa2); PK4(p1, 8, pa3);
;     ...
; }
.Lw1slow_g0a:
	v_max_f32_e32 v163, v162, v161
	v_sub_f32_e32 v161, v162, v163
	v_exp_f32_e32 v161, v161
	v_mov_b32_e32 v162, v163
	s_and_saveexec_b64 s[72:73], s[38:39]
	ds_write_b32 v213, v161 offset:128
	s_or_b64 exec, exec, s[72:73]
	s_waitcnt lgkmcnt(0)
	v_add_u32_e32 v194, s4, v215
	ds_read_b128 v[164:167], v194 offset:224
	ds_read_b128 v[168:171], v194 offset:192
	ds_read_b128 v[172:175], v194 offset:160
	ds_read_b128 v[176:179], v194 offset:128
	s_waitcnt lgkmcnt(0)
	v_pk_mul_f32 v[44:45], v[44:45], v[164:165]
	v_pk_mul_f32 v[40:41], v[40:41], v[168:169]
	v_pk_mul_f32 v[36:37], v[36:37], v[172:173]
	v_pk_mul_f32 v[46:47], v[46:47], v[166:167]
	v_pk_mul_f32 v[42:43], v[42:43], v[170:171]
	v_pk_mul_f32 v[38:39], v[38:39], v[174:175]
	v_pk_mul_f32 v[34:35], v[34:35], v[178:179]
	v_pk_mul_f32 v[32:33], v[32:33], v[176:177]
	v_pk_mul_f32 v[60:61], v[60:61], v[164:165]
	v_pk_mul_f32 v[56:57], v[56:57], v[168:169]
	v_pk_mul_f32 v[52:53], v[52:53], v[172:173]
	v_pk_mul_f32 v[62:63], v[62:63], v[166:167]
	v_pk_mul_f32 v[58:59], v[58:59], v[170:171]
	v_pk_mul_f32 v[54:55], v[54:55], v[174:175]
	v_pk_mul_f32 v[50:51], v[50:51], v[178:179]
	v_pk_mul_f32 v[48:49], v[48:49], v[176:177]
	v_pk_mul_f32 v[28:29], v[28:29], v[164:165]
	v_pk_mul_f32 v[24:25], v[24:25], v[168:169]
	v_pk_mul_f32 v[20:21], v[20:21], v[172:173]
	v_pk_mul_f32 v[30:31], v[30:31], v[166:167]
	v_pk_mul_f32 v[26:27], v[26:27], v[170:171]
	v_pk_mul_f32 v[22:23], v[22:23], v[174:175]
	v_pk_mul_f32 v[18:19], v[18:19], v[178:179]
	v_pk_mul_f32 v[16:17], v[16:17], v[176:177]
	v_pk_mul_f32 v[12:13], v[12:13], v[164:165]
	v_pk_mul_f32 v[8:9], v[8:9], v[168:169]
	v_pk_mul_f32 v[4:5], v[4:5], v[172:173]
	v_pk_mul_f32 v[14:15], v[14:15], v[166:167]
	v_pk_mul_f32 v[10:11], v[10:11], v[170:171]
	v_pk_mul_f32 v[6:7], v[6:7], v[174:175]
	v_pk_mul_f32 v[2:3], v[2:3], v[178:179]
	v_pk_mul_f32 v[0:1], v[0:1], v[176:177]
	v_mul_f32_e32 v156, v156, v161
	v_sub_f32_e32 v64, v64, v162
	v_exp_f32_e32 v64, v64
	v_sub_f32_e32 v65, v65, v162
	v_exp_f32_e32 v65, v65
	v_sub_f32_e32 v66, v66, v162
	v_exp_f32_e32 v66, v66
	v_add_f32_e32 v188, v65, v64
	v_sub_f32_e32 v67, v67, v162
	v_exp_f32_e32 v67, v67
	v_add_f32_e32 v188, v66, v188
	v_sub_f32_e32 v68, v68, v162
	v_exp_f32_e32 v68, v68
	v_add_f32_e32 v188, v67, v188
	v_sub_f32_e32 v69, v69, v162
	v_exp_f32_e32 v69, v69
	v_add_f32_e32 v188, v68, v188
	v_sub_f32_e32 v70, v70, v162
	v_exp_f32_e32 v70, v70
	v_add_f32_e32 v188, v69, v188
	v_sub_f32_e32 v71, v71, v162
	v_exp_f32_e32 v71, v71
	v_add_f32_e32 v188, v70, v188
	v_sub_f32_e32 v72, v72, v162
	v_exp_f32_e32 v72, v72
	v_add_f32_e32 v188, v71, v188
	v_sub_f32_e32 v73, v73, v162
	v_exp_f32_e32 v73, v73
	v_add_f32_e32 v188, v72, v188
	v_sub_f32_e32 v74, v74, v162
	v_exp_f32_e32 v74, v74
	v_add_f32_e32 v188, v73, v188
	v_sub_f32_e32 v75, v75, v162
	v_exp_f32_e32 v75, v75
	v_add_f32_e32 v188, v74, v188
	v_sub_f32_e32 v76, v76, v162
	v_exp_f32_e32 v76, v76
	v_add_f32_e32 v188, v75, v188
	v_sub_f32_e32 v77, v77, v162
	v_exp_f32_e32 v77, v77
	v_add_f32_e32 v188, v76, v188
	v_sub_f32_e32 v78, v78, v162
	v_exp_f32_e32 v78, v78
	v_add_f32_e32 v188, v77, v188
	v_sub_f32_e32 v79, v79, v162
	v_exp_f32_e32 v79, v79
	v_add_f32_e32 v188, v78, v188
	v_sub_f32_e32 v80, v80, v162
	v_exp_f32_e32 v80, v80
	v_add_f32_e32 v188, v79, v188
	v_sub_f32_e32 v81, v81, v162
	v_exp_f32_e32 v81, v81
	v_add_f32_e32 v188, v80, v188
	v_sub_f32_e32 v82, v82, v162
	v_exp_f32_e32 v82, v82
	v_add_f32_e32 v188, v81, v188
	v_sub_f32_e32 v83, v83, v162
	v_exp_f32_e32 v83, v83
	v_add_f32_e32 v188, v82, v188
	v_sub_f32_e32 v84, v84, v162
	v_exp_f32_e32 v84, v84
	v_add_f32_e32 v188, v83, v188
	v_sub_f32_e32 v85, v85, v162
	v_exp_f32_e32 v85, v85
	v_add_f32_e32 v188, v84, v188
	v_sub_f32_e32 v86, v86, v162
	v_exp_f32_e32 v86, v86
	v_add_f32_e32 v188, v85, v188
	v_sub_f32_e32 v87, v87, v162
	v_exp_f32_e32 v87, v87
	v_add_f32_e32 v188, v86, v188
	v_sub_f32_e32 v88, v88, v162
	v_exp_f32_e32 v88, v88
	v_add_f32_e32 v188, v87, v188
	v_sub_f32_e32 v89, v89, v162
	v_exp_f32_e32 v89, v89
	v_add_f32_e32 v188, v88, v188
	v_sub_f32_e32 v90, v90, v162
	v_exp_f32_e32 v90, v90
	v_add_f32_e32 v188, v89, v188
	v_sub_f32_e32 v91, v91, v162
	v_exp_f32_e32 v91, v91
	v_add_f32_e32 v188, v90, v188
	v_sub_f32_e32 v92, v92, v162
	v_exp_f32_e32 v92, v92
	v_add_f32_e32 v188, v91, v188
	v_sub_f32_e32 v93, v93, v162
	v_exp_f32_e32 v93, v93
	v_add_f32_e32 v188, v92, v188
	v_sub_f32_e32 v94, v94, v162
	v_exp_f32_e32 v94, v94
	v_add_f32_e32 v188, v93, v188
	v_sub_f32_e32 v95, v95, v162
	v_exp_f32_e32 v95, v95
	v_add_f32_e32 v188, v94, v188
	v_add_f32_e32 v188, v95, v188
	v_mov_b32_e32 v189, v188
	v_cvt_pk_bf16_f32 v64, v64, v65
	v_cvt_pk_bf16_f32 v65, v66, v67
	v_cvt_pk_bf16_f32 v66, v68, v69
	v_cvt_pk_bf16_f32 v67, v70, v71
	v_cvt_pk_bf16_f32 v68, v72, v73
	v_cvt_pk_bf16_f32 v69, v74, v75
	v_cvt_pk_bf16_f32 v70, v76, v77
	v_cvt_pk_bf16_f32 v71, v78, v79
	v_cvt_pk_bf16_f32 v72, v80, v81
	v_cvt_pk_bf16_f32 v73, v82, v83
	v_cvt_pk_bf16_f32 v74, v84, v85
	v_cvt_pk_bf16_f32 v75, v86, v87
	v_cvt_pk_bf16_f32 v76, v88, v89
	v_cvt_pk_bf16_f32 v77, v90, v91
	v_cvt_pk_bf16_f32 v78, v92, v93
	v_cvt_pk_bf16_f32 v79, v94, v95
	v_permlane32_swap_b32_e32 v188, v189
	v_add_f32_e32 v156, v156, v188
	v_add_f32_e32 v156, v156, v189
	s_branch .Lw1join_g0a
; __device__ __forceinline__ void partialSM(f32x16& p0, f32x16& p1, float& m_reg, float& alpha) {
;   constexpr float THR2 = THR * 1.4426950408889634f;
;   float pmax = p0[0];
; #pragma unroll
;   for (int r = 1; r < 16; ++r) pmax = fmaxf(pmax, p0[r]);
; #pragma unroll
;   for (int r = 0; r < 16; ++r) pmax = fmaxf(pmax, p1[r]);
;   { auto rr = __builtin_amdgcn_permlane32_swap(__float_as_uint(pmax), __float_as_uint(pmax), false, false);
;     pmax = fmaxf(__uint_as_float(rr[0]), __uint_as_float(rr[1])); }
;   float mn;
;   if (__builtin_expect(__all(pmax - m_reg <= THR2), 1)) { mn = m_reg; alpha = 1.f; }
;   else { mn = fmaxf(m_reg, pmax); alpha = __builtin_amdgcn_exp2f(m_reg - mn); m_reg = mn; }
; #pragma unroll
;   for (int r = 0; r < 16; ++r) { p0[r] -= mn; p1[r] -= mn; }
; #pragma unroll
;   for (int r = 0; r < 16; ++r) p0[r] = __builtin_amdgcn_exp2f(p0[r]);
; }
; __device__ __forceinline__ void finishSM(f32x16& p0, f32x16& p1, float alpha, float& l_reg, bf16x8& pa0, bf16x8& pa1, bf16x8& pa2, bf16x8& pa3) {
; #pragma unroll
;   for (int r = 0; r < 16; ++r) p1[r] = __builtin_amdgcn_exp2f(p1[r]);
;   float ps = 0;
; #pragma unroll
;   for (int r = 0; r < 16; ++r) ps += p0[r];
; #pragma unroll
;   for (int r = 0; r < 16; ++r) ps += p1[r];
;   { auto rr = __builtin_amdgcn_permlane32_swap(__float_as_uint(ps), __float_as_uint(ps), false, false);
;     ps = __uint_as_float(rr[0]) + __uint_as_float(rr[1]); }
;   l_reg = l_reg * alpha + ps;
;     ...
;   PK4(p0, 0, pa0); PK4(p0, 8, pa1); PK4(p1, 0, pa2); PK4(p1, 8, pa3);
;     ...
; }
.Lw1slow_g0b:
	v_max_f32_e32 v153, v162, v152
	v_sub_f32_e32 v152, v162, v153
	v_exp_f32_e32 v152, v152
	v_mov_b32_e32 v162, v153
	s_and_saveexec_b64 s[72:73], s[38:39]
	ds_write_b32 v213, v152 offset:128
	s_or_b64 exec, exec, s[72:73]
	s_waitcnt lgkmcnt(0)
	v_add_u32_e32 v154, s4, v215
	ds_read_b128 v[166:169], v154 offset:224
	ds_read_b128 v[170:173], v154 offset:192
	ds_read_b128 v[174:177], v154 offset:160
	ds_read_b128 v[188:191], v154 offset:128
	s_waitcnt lgkmcnt(0)
	v_pk_mul_f32 v[44:45], v[44:45], v[166:167]
	v_pk_mul_f32 v[40:41], v[40:41], v[170:171]
	v_pk_mul_f32 v[36:37], v[36:37], v[174:175]
	v_pk_mul_f32 v[46:47], v[46:47], v[168:169]
	v_pk_mul_f32 v[42:43], v[42:43], v[172:173]
	v_pk_mul_f32 v[38:39], v[38:39], v[176:177]
	v_pk_mul_f32 v[34:35], v[34:35], v[190:191]
	v_pk_mul_f32 v[32:33], v[32:33], v[188:189]
	v_pk_mul_f32 v[60:61], v[60:61], v[166:167]
	v_pk_mul_f32 v[56:57], v[56:57], v[170:171]
	v_pk_mul_f32 v[52:53], v[52:53], v[174:175]
	v_pk_mul_f32 v[62:63], v[62:63], v[168:169]
	v_pk_mul_f32 v[58:59], v[58:59], v[172:173]
	v_pk_mul_f32 v[54:55], v[54:55], v[176:177]
	v_pk_mul_f32 v[50:51], v[50:51], v[190:191]
	v_pk_mul_f32 v[48:49], v[48:49], v[188:189]
	v_pk_mul_f32 v[28:29], v[28:29], v[166:167]
	v_pk_mul_f32 v[24:25], v[24:25], v[170:171]
	v_pk_mul_f32 v[20:21], v[20:21], v[174:175]
	v_pk_mul_f32 v[30:31], v[30:31], v[168:169]
	v_pk_mul_f32 v[26:27], v[26:27], v[172:173]
	v_pk_mul_f32 v[22:23], v[22:23], v[176:177]
	v_pk_mul_f32 v[18:19], v[18:19], v[190:191]
	v_pk_mul_f32 v[16:17], v[16:17], v[188:189]
	v_pk_mul_f32 v[12:13], v[12:13], v[166:167]
	v_pk_mul_f32 v[8:9], v[8:9], v[170:171]
	v_pk_mul_f32 v[4:5], v[4:5], v[174:175]
	v_pk_mul_f32 v[14:15], v[14:15], v[168:169]
	v_pk_mul_f32 v[10:11], v[10:11], v[172:173]
	v_pk_mul_f32 v[6:7], v[6:7], v[176:177]
	v_pk_mul_f32 v[2:3], v[2:3], v[190:191]
	v_pk_mul_f32 v[0:1], v[0:1], v[188:189]
	v_mul_f32_e32 v156, v156, v152
	v_sub_f32_e32 v64, v64, v162
	v_exp_f32_e32 v64, v64
	v_sub_f32_e32 v65, v65, v162
	v_exp_f32_e32 v65, v65
	v_sub_f32_e32 v66, v66, v162
	v_exp_f32_e32 v66, v66
	v_add_f32_e32 v190, v65, v64
	v_sub_f32_e32 v67, v67, v162
	v_exp_f32_e32 v67, v67
	v_add_f32_e32 v190, v66, v190
	v_sub_f32_e32 v68, v68, v162
	v_exp_f32_e32 v68, v68
	v_add_f32_e32 v190, v67, v190
	v_sub_f32_e32 v69, v69, v162
	v_exp_f32_e32 v69, v69
	v_add_f32_e32 v190, v68, v190
	v_sub_f32_e32 v70, v70, v162
	v_exp_f32_e32 v70, v70
	v_add_f32_e32 v190, v69, v190
	v_sub_f32_e32 v71, v71, v162
	v_exp_f32_e32 v71, v71
	v_add_f32_e32 v190, v70, v190
	v_sub_f32_e32 v72, v72, v162
	v_exp_f32_e32 v72, v72
	v_add_f32_e32 v190, v71, v190
	v_sub_f32_e32 v73, v73, v162
	v_exp_f32_e32 v73, v73
	v_add_f32_e32 v190, v72, v190
	v_sub_f32_e32 v74, v74, v162
	v_exp_f32_e32 v74, v74
	v_add_f32_e32 v190, v73, v190
	v_sub_f32_e32 v75, v75, v162
	v_exp_f32_e32 v75, v75
	v_add_f32_e32 v190, v74, v190
	v_sub_f32_e32 v76, v76, v162
	v_exp_f32_e32 v153, v76
	v_add_f32_e32 v190, v75, v190
	v_sub_f32_e32 v77, v77, v162
	v_exp_f32_e32 v154, v77
	v_add_f32_e32 v190, v153, v190
	v_sub_f32_e32 v78, v78, v162
	v_exp_f32_e32 v155, v78
	v_add_f32_e32 v190, v154, v190
	v_sub_f32_e32 v79, v79, v162
	v_exp_f32_e32 v165, v79
	v_add_f32_e32 v190, v155, v190
	v_sub_f32_e32 v80, v80, v162
	v_exp_f32_e32 v80, v80
	v_add_f32_e32 v190, v165, v190
	v_sub_f32_e32 v81, v81, v162
	v_exp_f32_e32 v81, v81
	v_add_f32_e32 v190, v80, v190
	v_sub_f32_e32 v82, v82, v162
	v_exp_f32_e32 v82, v82
	v_add_f32_e32 v190, v81, v190
	v_sub_f32_e32 v83, v83, v162
	v_exp_f32_e32 v83, v83
	v_add_f32_e32 v190, v82, v190
	v_sub_f32_e32 v84, v84, v162
	v_exp_f32_e32 v84, v84
	v_add_f32_e32 v190, v83, v190
	v_sub_f32_e32 v85, v85, v162
	v_exp_f32_e32 v85, v85
	v_add_f32_e32 v190, v84, v190
	v_sub_f32_e32 v86, v86, v162
	v_exp_f32_e32 v86, v86
	v_add_f32_e32 v190, v85, v190
	v_sub_f32_e32 v87, v87, v162
	v_exp_f32_e32 v87, v87
	v_add_f32_e32 v190, v86, v190
	v_sub_f32_e32 v88, v88, v162
	v_exp_f32_e32 v88, v88
	v_add_f32_e32 v190, v87, v190
	v_sub_f32_e32 v89, v89, v162
	v_exp_f32_e32 v89, v89
	v_add_f32_e32 v190, v88, v190
	v_sub_f32_e32 v90, v90, v162
	v_exp_f32_e32 v90, v90
	v_add_f32_e32 v190, v89, v190
	v_sub_f32_e32 v91, v91, v162
	v_exp_f32_e32 v91, v91
	v_add_f32_e32 v190, v90, v190
	v_sub_f32_e32 v92, v92, v162
	v_exp_f32_e32 v92, v92
	v_add_f32_e32 v190, v91, v190
	v_sub_f32_e32 v93, v93, v162
	v_exp_f32_e32 v93, v93
	v_add_f32_e32 v190, v92, v190
	v_sub_f32_e32 v94, v94, v162
	v_exp_f32_e32 v94, v94
	v_add_f32_e32 v190, v93, v190
	v_sub_f32_e32 v95, v95, v162
	v_exp_f32_e32 v95, v95
	v_add_f32_e32 v190, v94, v190
	v_add_f32_e32 v190, v95, v190
	v_mov_b32_e32 v191, v190
	v_cvt_pk_bf16_f32 v76, v64, v65
	v_cvt_pk_bf16_f32 v77, v66, v67
	v_cvt_pk_bf16_f32 v78, v68, v69
	v_cvt_pk_bf16_f32 v79, v70, v71
	v_cvt_pk_bf16_f32 v72, v72, v73
	v_cvt_pk_bf16_f32 v73, v74, v75
	v_cvt_pk_bf16_f32 v74, v153, v154
	v_cvt_pk_bf16_f32 v75, v155, v165
	v_cvt_pk_bf16_f32 v68, v80, v81
	v_cvt_pk_bf16_f32 v69, v82, v83
	v_cvt_pk_bf16_f32 v70, v84, v85
	v_cvt_pk_bf16_f32 v71, v86, v87
	v_cvt_pk_bf16_f32 v64, v88, v89
	v_cvt_pk_bf16_f32 v65, v90, v91
	v_cvt_pk_bf16_f32 v66, v92, v93
	v_cvt_pk_bf16_f32 v67, v94, v95
	v_permlane32_swap_b32_e32 v190, v191
	v_add_f32_e32 v156, v156, v190
	v_add_f32_e32 v156, v156, v191
	s_branch .Lw1join_g0b
